# hand-scheduled attention loop + early K/V prologue loads
# speedup vs baseline: 1.0189x; 1.0189x over previous
; __device__ __forceinline__ int ltid() { int t = threadIdx.x; asm volatile("" : "+v"(t)); return t; }
; #define LAS __attribute__((address_space(3)))
; __device__ __forceinline__ void attn_unit(CArgs a, int layer, int unit, LAS unsigned char* lds) {
;     const int tid = ltid(), lane = tid & 63, wid = tid >> 6, r32 = lane & 31, hi = lane >> 5;
;     const unsigned char* WSB = a->ws;
;     const int qb = unit & 7, bh = unit >> 3, h = bh & 7, b = bh >> 3;
;     const bf16_t* Kg = (const bf16_t*)(a->ws + WS_KF) + (size_t)bh * SEQ * 96;
;     const bf16_t* Vg = (const bf16_t*)(a->ws + WS_VT) + (size_t)bh * SEQ * 64;
;     const float2* cst = (const float2*)(a->ws + WS_CS);
;     const float* qhn = a->mla_qhn + layer * 96;
;     LAS float* wsf = (LAS float*)(lds + AT_WS) + wid * 64;
;     const int qrow = b * SEQ + qb * 256 + wid * 32 + r32;
;     bf16x8 qf[6]; float mref;
;     {
;         const bf16_t* qp = (const bf16_t*)(a->ws + WS_QR) + (size_t)qrow * 768 + h * 96;
;         float q[6][8]; float ss = 0.f;
; #pragma unroll
;         for (int s = 0; s < 6; ++s) { unpack8(*(const u32x4*)(qp + 16 * s + 8 * hi), q[s]);
; #pragma unroll
;             for (int e = 0; e < 8; ++e) ss += q[s][e] * q[s][e]; }
;         ss += __shfl_xor(ss, 32);
;         const float rq = rsqrtf(ss * (1.f / 96.f) + EPS);
; #pragma unroll
;         for (int s = 0; s < 6; ++s)
; #pragma unroll
;             for (int e = 0; e < 8; ++e) q[s][e] *= rq * qhn[16 * s + 8 * hi + e];
; #pragma unroll
;         for (int e = 0; e < 8; ++e) { const float2 c = cst[(size_t)qrow * 16 + 8 * hi + e]; const float x1 = q[4][e], x2 = q[5][e];
.LBB0_66:
	s_lshl_b32 s2, s10, 1
	v_mov_b32_e32 v159, v244
	s_and_b32 s2, s2, 0x1fe
	s_ashr_i32 s3, s10, 8
	s_load_dwordx2 s[60:61], s[6:7], 0xe8
	s_load_dwordx4 s[40:43], s[6:7], 0x90
	s_add_i32 s12, s2, s3
	s_ashr_i32 s2, s12, 3
	s_ashr_i32 s3, s2, 31
	s_and_b32 s11, s2, 7
	s_lshl_b64 s[22:23], s[2:3], 18
	s_waitcnt lgkmcnt(0)
	s_add_u32 s3, s60, s22
	s_addc_u32 s13, s61, s23
	s_add_u32 s18, s3, 0x17a00000
	s_addc_u32 s19, s13, 0
	s_lshl_b32 s3, s12, 5
	s_lshl_b32 s12, s12, 8
	s_and_b32 s3, s3, 0xfffff800
	s_and_b32 s12, s12, 0x700
	v_ashrrev_i32_e32 v0, 1, v159
	s_or_b32 s3, s3, s12
	v_and_b32_e32 v162, 0xffffffe0, v0
	v_and_b32_e32 v161, 31, v159
	v_add_u32_e32 v158, s3, v162
	v_or_b32_e32 v2, v158, v161
	v_mov_b64_e32 v[4:5], s[60:61]
	s_movk_i32 s3, 0x600
	v_mad_i64_i32 v[4:5], s[12:13], v2, s3, v[4:5]
	s_mul_hi_i32 s3, s2, 0x60000
	s_mul_i32 s2, s2, 0x60000
	s_add_u32 s2, s60, s2
	v_bfe_u32 v160, v159, 5, 1
	s_mul_i32 s34, s11, 0xc0
	v_ashrrev_i32_e32 v3, 31, v2
	s_addc_u32 s3, s61, s3
	v_lshl_add_u64 v[4:5], v[4:5], 0, s[34:35]
	v_lshlrev_b32_e32 v0, 4, v160
	v_lshlrev_b64 v[2:3], 7, v[2:3]
	s_add_u32 s20, s2, 0x16200000
	v_lshl_add_u64 v[14:15], v[4:5], 0, v[0:1]
	s_mov_b64 s[12:13], 0x14a00000
	v_lshl_add_u64 v[2:3], s[60:61], 0, v[2:3]
	v_lshlrev_b32_e32 v0, 6, v160
	s_addc_u32 s21, s3, 0
	v_lshl_add_u64 v[16:17], v[14:15], 0, s[12:13]
	v_lshl_add_u64 v[26:27], v[2:3], 0, v[0:1]
	s_mov_b64 s[12:13], 0x200000
	s_add_u32 s24, s40, s16
	v_lshl_add_u64 v[10:11], v[26:27], 0, s[12:13]
	s_addc_u32 s25, s41, s17
	v_and_b32_e32 v49, 32, v159
	global_load_dwordx4 v[50:53], v[16:17], off offset:128
	global_load_dwordx4 v[54:57], v[16:17], off offset:160
	global_load_dwordx4 v[6:9], v[10:11], off offset:16
	global_load_dwordx4 v[2:5], v[10:11], off offset:48
	s_nop 0
	global_load_dwordx4 v[10:13], v[10:11], off offset:32
	s_nop 0
	global_load_dwordx4 v[18:21], v49, s[24:25] offset:320
	global_load_dwordx4 v[58:61], v[16:17], off offset:96
	global_load_dwordx4 v[62:65], v[16:17], off offset:64
	v_and_b32_e32 v0, 64, v247
	v_xor_b32_e32 v22, 32, v247
	v_add_u32_e32 v48, 64, v0
	v_cmp_lt_i32_e32 vcc, v22, v48
	s_mov_b32 s2, 0x14a00000
	global_load_dwordx4 v[66:69], v[16:17], off offset:32
	v_cndmask_b32_e32 v16, v247, v22, vcc
	v_add_co_u32_e32 v14, vcc, s2, v14
	s_mov_b32 s2, 0x200000
	s_nop 0
	v_addc_co_u32_e32 v15, vcc, 0, v15, vcc
	global_load_dwordx4 v[70:73], v[14:15], off
	global_load_dwordx4 v[22:25], v49, s[24:25] offset:336
	v_add_co_u32_e32 v14, vcc, s2, v26
	v_lshlrev_b32_e32 v164, 2, v16
	s_nop 0
	v_addc_co_u32_e32 v15, vcc, 0, v27, vcc
	global_load_dwordx4 v[30:33], v49, s[24:25] offset:272
	global_load_dwordx4 v[26:29], v49, s[24:25] offset:256
	s_nop 0
	global_load_dwordx4 v[14:17], v[14:15], off
	v_and_b32_e32 v0, 63, v159
	s_add_u32 s2, s42, s16
	s_addc_u32 s3, s43, s17
	v_lshlrev_b32_e32 v165, 2, v161
	s_waitcnt vmcnt(13)
	v_lshlrev_b32_e32 v38, 16, v53
	v_and_b32_e32 v39, 0xffff0000, v53
	s_waitcnt vmcnt(12)
	v_lshlrev_b32_e32 v36, 16, v57
	v_and_b32_e32 v37, 0xffff0000, v57
	v_lshlrev_b32_e32 v44, 16, v52
	v_and_b32_e32 v45, 0xffff0000, v52
	v_lshlrev_b32_e32 v40, 16, v56
	v_and_b32_e32 v41, 0xffff0000, v56
	v_lshlrev_b32_e32 v46, 16, v51
	s_waitcnt vmcnt(10)
	v_mov_b32_e32 v34, v2
	v_mov_b32_e32 v35, v4
	v_mov_b32_e32 v4, v3
	s_waitcnt vmcnt(9)
	v_mov_b32_e32 v2, v10
	v_mov_b32_e32 v3, v12
	v_mov_b32_e32 v12, v11
	v_and_b32_e32 v11, 0xffff0000, v55
	v_and_b32_e32 v10, 16, v51
	v_lshlrev_b32_e32 v98, 16, v55
	v_and_b32_e32 v99, 0xffff0000, v51
	v_lshlrev_b32_e32 v102, 16, v50
	v_and_b32_e32 v103, 0xffff0000, v50
	v_lshlrev_b32_e32 v106, 16, v54
	v_and_b32_e32 v107, 0xffff0000, v54
	s_waitcnt vmcnt(7)
	v_lshlrev_b32_e32 v110, 16, v61
	v_and_b32_e32 v111, 0xffff0000, v61
	global_load_dwordx4 v[50:53], v49, s[24:25] offset:208
	global_load_dwordx4 v[54:57], v49, s[24:25] offset:192
	v_lshlrev_b32_e32 v114, 16, v60
	v_and_b32_e32 v115, 0xffff0000, v60
	v_lshlrev_b32_e32 v118, 16, v59
	v_and_b32_e32 v119, 0xffff0000, v59
	v_lshlrev_b32_e32 v122, 16, v58
	v_and_b32_e32 v123, 0xffff0000, v58
	s_waitcnt vmcnt(8)
	v_lshlrev_b32_e32 v126, 16, v65
	v_and_b32_e32 v127, 0xffff0000, v65
	global_load_dwordx4 v[58:61], v49, s[24:25] offset:144
	global_load_dwordx4 v[74:77], v49, s[24:25] offset:128
	v_lshlrev_b32_e32 v130, 16, v64
	v_and_b32_e32 v131, 0xffff0000, v64
	v_lshlrev_b32_e32 v134, 16, v63
	v_and_b32_e32 v135, 0xffff0000, v63
	v_lshlrev_b32_e32 v138, 16, v62
	v_and_b32_e32 v139, 0xffff0000, v62
	global_load_dwordx4 v[62:65], v49, s[24:25] offset:80
	global_load_dwordx4 v[78:81], v49, s[24:25] offset:64
	global_load_dwordx4 v[82:85], v49, s[24:25] offset:16
	global_load_dwordx4 v[86:89], v49, s[24:25]
	s_waitcnt vmcnt(12)
; __device__ __forceinline__ u32x4 pack8(const float (&f)[8]) { u32x4 v; v.x = cvt_pk_bf16(f[0], f[1]); v.y = cvt_pk_bf16(f[2], f[3]); v.z = cvt_pk_bf16(f[4], f[5]); v.w = cvt_pk_bf16(f[6], f[7]); return v; }
; __device__ __forceinline__ void attn_unit(CArgs a, int layer, int unit, LAS unsigned char* lds) {
;     ...
;         float q[6][8]; float ss = 0.f;
; #pragma unroll
;         for (int s = 0; s < 6; ++s) { unpack8(*(const u32x4*)(qp + 16 * s + 8 * hi), q[s]);
; #pragma unroll
;             for (int e = 0; e < 8; ++e) ss += q[s][e] * q[s][e]; }
;         ss += __shfl_xor(ss, 32);
;         const float rq = rsqrtf(ss * (1.f / 96.f) + EPS);
; #pragma unroll
;         for (int s = 0; s < 6; ++s)
; #pragma unroll
;             for (int e = 0; e < 8; ++e) q[s][e] *= rq * qhn[16 * s + 8 * hi + e];
; #pragma unroll
;         for (int e = 0; e < 8; ++e) { const float2 c = cst[(size_t)qrow * 16 + 8 * hi + e]; const float x1 = q[4][e], x2 = q[5][e];
;             q[4][e] = x1 * c.x - x2 * c.y; q[5][e] = x1 * c.y + x2 * c.x; }
;         float qn2 = 0.f;
; #pragma unroll
;         for (int s = 0; s < 6; ++s) {
; #pragma unroll
;             for (int e = 0; e < 8; ++e) { q[s][e] *= QK_SCALE; qn2 += q[s][e] * q[s][e]; }
;             qf[s] = __builtin_bit_cast(bf16x8, pack8(q[s]));
;         }
;         qn2 += __shfl_xor(qn2, 32);
;         const float* khn = a->mla_khn + layer * 96;
;         float gm = fmaxf(fabsf(khn[lane]), fabsf(khn[64 + (lane & 31)]));
	v_lshlrev_b32_e32 v172, 16, v70
	v_and_b32_e32 v173, 0xffff0000, v70
	v_lshlrev_b32_e32 v168, 16, v71
	v_and_b32_e32 v169, 0xffff0000, v71
	v_pk_mul_f32 v[70:71], v[172:173], v[172:173]
	v_mov_b32_e32 v100, v20
	v_pk_mul_f32 v[170:171], v[168:169], v[168:169]
	v_add_f32_e32 v20, v70, v71
	v_lshlrev_b32_e32 v166, 16, v72
	v_and_b32_e32 v167, 0xffff0000, v72
	v_add_f32_e32 v20, v170, v20
	v_lshlrev_b32_e32 v154, 16, v73
	v_and_b32_e32 v155, 0xffff0000, v73
	v_pk_mul_f32 v[72:73], v[166:167], v[166:167]
	v_add_f32_e32 v20, v171, v20
	v_add_f32_e32 v20, v72, v20
	v_pk_mul_f32 v[156:157], v[154:155], v[154:155]
	v_add_f32_e32 v20, v73, v20
	v_lshlrev_b32_e32 v152, 16, v66
	v_and_b32_e32 v153, 0xffff0000, v66
	v_add_f32_e32 v20, v156, v20
	v_lshlrev_b32_e32 v148, 16, v67
	v_and_b32_e32 v149, 0xffff0000, v67
	v_pk_mul_f32 v[66:67], v[152:153], v[152:153]
	v_add_f32_e32 v20, v157, v20
	v_add_f32_e32 v20, v66, v20
	v_pk_mul_f32 v[150:151], v[148:149], v[148:149]
	v_add_f32_e32 v20, v67, v20
	v_lshlrev_b32_e32 v146, 16, v68
	v_and_b32_e32 v147, 0xffff0000, v68
	v_add_f32_e32 v20, v150, v20
	v_lshlrev_b32_e32 v142, 16, v69
	v_and_b32_e32 v143, 0xffff0000, v69
	v_pk_mul_f32 v[68:69], v[146:147], v[146:147]
	v_add_f32_e32 v20, v151, v20
	v_add_f32_e32 v20, v68, v20
	v_pk_mul_f32 v[144:145], v[142:143], v[142:143]
	v_add_f32_e32 v20, v69, v20
	v_add_f32_e32 v20, v144, v20
	v_pk_mul_f32 v[140:141], v[138:139], v[138:139]
	v_add_f32_e32 v20, v145, v20
	v_add_f32_e32 v20, v140, v20
	v_pk_mul_f32 v[136:137], v[134:135], v[134:135]
	v_add_f32_e32 v20, v141, v20
	v_add_f32_e32 v20, v136, v20
	v_pk_mul_f32 v[132:133], v[130:131], v[130:131]
	v_add_f32_e32 v20, v137, v20
	v_add_f32_e32 v20, v132, v20
	v_pk_mul_f32 v[128:129], v[126:127], v[126:127]
	v_add_f32_e32 v20, v133, v20
	v_add_f32_e32 v20, v128, v20
	v_pk_mul_f32 v[124:125], v[122:123], v[122:123]
	v_add_f32_e32 v20, v129, v20
	v_add_f32_e32 v20, v124, v20
	v_pk_mul_f32 v[120:121], v[118:119], v[118:119]
	v_add_f32_e32 v20, v125, v20
	v_add_f32_e32 v20, v120, v20
	v_pk_mul_f32 v[116:117], v[114:115], v[114:115]
	v_add_f32_e32 v20, v121, v20
	v_add_f32_e32 v20, v116, v20
	v_pk_mul_f32 v[112:113], v[110:111], v[110:111]
	v_add_f32_e32 v20, v117, v20
	v_add_f32_e32 v20, v112, v20
	v_pk_mul_f32 v[104:105], v[102:103], v[102:103]
	v_add_f32_e32 v20, v113, v20
	v_add_f32_e32 v20, v104, v20
	v_add_f32_e32 v20, v105, v20
	v_fmac_f32_e32 v20, v46, v46
	v_pk_mul_f32 v[94:95], v[44:45], v[44:45]
	v_fmac_f32_e32 v20, v99, v99
	v_add_f32_e32 v20, v94, v20
	v_pk_mul_f32 v[90:91], v[38:39], v[38:39]
	v_add_f32_e32 v20, v95, v20
	v_add_f32_e32 v20, v90, v20
	v_pk_mul_f32 v[108:109], v[106:107], v[106:107]
	v_add_f32_e32 v20, v91, v20
	v_mov_b32_e32 v47, v11
	v_pk_mov_b32 v[10:11], v[10:11], v[98:99] op_sel:[1,0]
	v_add_f32_e32 v20, v108, v20
	v_pk_mul_f32 v[10:11], v[10:11], v[10:11]
	v_add_f32_e32 v20, v109, v20
	v_add_f32_e32 v11, v11, v20
	v_pk_mul_f32 v[96:97], v[40:41], v[40:41]
	v_add_f32_e32 v10, v10, v11
	v_add_f32_e32 v10, v96, v10
	v_pk_mul_f32 v[92:93], v[36:37], v[36:37]
	v_add_f32_e32 v10, v97, v10
	v_add_f32_e32 v10, v92, v10
	v_add_f32_e32 v20, v93, v10
	ds_bpermute_b32 v49, v164, v20
	s_waitcnt vmcnt(9)
	v_mov_b32_e32 v101, v29
	v_mov_b32_e32 v29, v21
	s_waitcnt vmcnt(8)
	v_mov_b32_e32 v66, v14
	v_mov_b32_e32 v67, v16
	s_waitcnt lgkmcnt(0)
	v_add_f32_e32 v20, v20, v49
	v_fmamk_f32 v20, v20, 0x3c2aaaab, v245
	v_mul_f32_e32 v21, 0x4b800000, v20
	v_cmp_gt_f32_e32 vcc, s83, v20
	v_mov_b32_e32 v16, v15
	v_mov_b32_e32 v10, v6
	v_cndmask_b32_e32 v20, v20, v21, vcc
	v_rsq_f32_e32 v20, v20
	v_mov_b32_e32 v11, v9
	v_mov_b32_e32 v42, v7
	v_mov_b32_e32 v43, v8
	v_mul_f32_e32 v14, 0x45800000, v20
	v_cndmask_b32_e32 v14, v20, v14, vcc
	v_pk_mul_f32 v[26:27], v[26:27], v[14:15] op_sel_hi:[1,0]
	s_waitcnt vmcnt(0)
	v_pk_mul_f32 v[20:21], v[86:87], v[14:15] op_sel_hi:[1,0]
	v_pk_mul_f32 v[52:53], v[52:53], v[14:15] op_sel_hi:[1,0]
	v_pk_mul_f32 v[86:87], v[26:27], v[102:103]
	v_pk_mul_f32 v[26:27], v[30:31], v[14:15] op_sel_hi:[1,0]
	v_lshlrev_b32_e32 v30, 2, v0
	v_pk_mul_f32 v[52:53], v[52:53], v[110:111]
	global_load_dword v49, v30, s[2:3]
	global_load_dword v110, v165, s[2:3] offset:256
	v_pk_mul_f32 v[18:19], v[18:19], v[14:15] op_sel_hi:[1,0]
	v_pk_mul_f32 v[68:69], v[88:89], v[14:15] op_sel_hi:[1,0]
	v_pk_mul_f32 v[88:89], v[18:19], v[106:107]
	v_pk_mul_f32 v[18:19], v[100:101], v[14:15] op_sel_hi:[1,0]
	v_pk_mul_f32 v[70:71], v[82:83], v[14:15] op_sel_hi:[1,0]
	v_pk_mul_f32 v[96:97], v[18:19], v[98:99]
	v_pk_mul_f32 v[18:19], v[28:29], v[14:15] op_sel_hi:[1,0]
	v_pk_mul_f32 v[72:73], v[84:85], v[14:15] op_sel_hi:[1,0]
	v_pk_mul_f32 v[78:79], v[78:79], v[14:15] op_sel_hi:[1,0]
	v_pk_mul_f32 v[80:81], v[80:81], v[14:15] op_sel_hi:[1,0]
	v_pk_mul_f32 v[62:63], v[62:63], v[14:15] op_sel_hi:[1,0]
	v_pk_mul_f32 v[64:65], v[64:65], v[14:15] op_sel_hi:[1,0]
	v_pk_mul_f32 v[74:75], v[74:75], v[14:15] op_sel_hi:[1,0]
	v_pk_mul_f32 v[76:77], v[76:77], v[14:15] op_sel_hi:[1,0]
	v_pk_mul_f32 v[58:59], v[58:59], v[14:15] op_sel_hi:[1,0]
	v_pk_mul_f32 v[60:61], v[60:61], v[14:15] op_sel_hi:[1,0]
	v_pk_mul_f32 v[54:55], v[54:55], v[14:15] op_sel_hi:[1,0]
	v_pk_mul_f32 v[56:57], v[56:57], v[14:15] op_sel_hi:[1,0]
	v_pk_mul_f32 v[50:51], v[50:51], v[14:15] op_sel_hi:[1,0]
	v_pk_mul_f32 v[44:45], v[26:27], v[44:45]
	v_pk_mul_f32 v[26:27], v[32:33], v[14:15] op_sel_hi:[1,0]
	v_pk_mul_f32 v[46:47], v[18:19], v[46:47]
	v_pk_mul_f32 v[18:19], v[22:23], v[14:15] op_sel_hi:[1,0]
	v_pk_mul_f32 v[14:15], v[24:25], v[14:15] op_sel_hi:[1,0]
	v_pk_mul_f32 v[10:11], v[10:11], v[96:97]
	v_pk_mul_f32 v[36:37], v[14:15], v[36:37]
; __device__ __forceinline__ u32x4 pack8(const float (&f)[8]) { u32x4 v; v.x = cvt_pk_bf16(f[0], f[1]); v.y = cvt_pk_bf16(f[2], f[3]); v.z = cvt_pk_bf16(f[4], f[5]); v.w = cvt_pk_bf16(f[6], f[7]); return v; }
; __device__ __forceinline__ void attn_unit(CArgs a, int layer, int unit, LAS unsigned char* lds) {
;     ...
;         for (int e = 0; e < 8; ++e) { const float2 c = cst[(size_t)qrow * 16 + 8 * hi + e]; const float x1 = q[4][e], x2 = q[5][e];
;             q[4][e] = x1 * c.x - x2 * c.y; q[5][e] = x1 * c.y + x2 * c.x; }
;         float qn2 = 0.f;
; #pragma unroll
;         for (int s = 0; s < 6; ++s) {
; #pragma unroll
;             for (int e = 0; e < 8; ++e) { q[s][e] *= QK_SCALE; qn2 += q[s][e] * q[s][e]; }
;             qf[s] = __builtin_bit_cast(bf16x8, pack8(q[s]));
;         }
;         qn2 += __shfl_xor(qn2, 32);
;         const float* khn = a->mla_khn + layer * 96;
;         float gm = fmaxf(fabsf(khn[lane]), fabsf(khn[64 + (lane & 31)]));
; #pragma unroll
;         for (int o = 1; o < 64; o <<= 1) gm = fmaxf(gm, __shfl_xor(gm, o));
;         mref = 1.02f * sqrtf(qn2) * 9.797958971f * gm;
;     ...
;     __syncthreads();
	v_pk_mul_f32 v[14:15], v[66:67], v[88:89]
	v_pk_fma_f32 v[42:43], v[42:43], v[46:47], v[10:11]
	v_pk_fma_f32 v[102:103], v[16:17], v[86:87], v[14:15]
	v_pk_mul_f32 v[16:17], v[16:17], v[88:89]
	v_mov_b32_e32 v88, v46
	v_pk_fma_f32 v[16:17], v[66:67], v[86:87], v[16:17] neg_lo:[0,0,1] neg_hi:[0,0,1]
	v_mov_b32_e32 v87, v97
	v_mov_b32_e32 v46, v7
	v_mov_b32_e32 v97, v9
	v_mov_b32_e32 v86, v6
	v_mov_b32_e32 v89, v8
	v_pk_mul_f32 v[6:7], v[46:47], v[96:97]
	v_pk_mul_f32 v[40:41], v[18:19], v[40:41]
	v_pk_fma_f32 v[6:7], v[86:87], v[88:89], v[6:7] neg_lo:[0,0,1] neg_hi:[0,0,1]
	v_pk_mul_f32 v[10:11], v[44:45], v[12:13]
	v_pk_mul_f32 v[86:87], v[6:7], s[30:31] op_sel_hi:[1,0]
	v_pk_mul_f32 v[6:7], v[40:41], v[12:13]
	v_pk_mul_f32 v[20:21], v[20:21], v[172:173]
	v_pk_fma_f32 v[104:105], v[40:41], v[2:3], v[10:11]
	v_pk_fma_f32 v[2:3], v[44:45], v[2:3], v[6:7] neg_lo:[0,0,1] neg_hi:[0,0,1]
	v_pk_mul_f32 v[68:69], v[68:69], v[168:169]
	v_pk_mul_f32 v[38:39], v[26:27], v[38:39]
	v_pk_mul_f32 v[22:23], v[20:21], s[30:31] op_sel_hi:[1,0]
	v_pk_mul_f32 v[96:97], v[2:3], s[30:31] op_sel_hi:[1,0]
	v_pk_mul_f32 v[2:3], v[36:37], v[4:5]
	v_pk_mul_f32 v[108:109], v[22:23], v[22:23]
	v_pk_mul_f32 v[24:25], v[68:69], s[30:31] op_sel_hi:[1,0]
	v_pk_fma_f32 v[2:3], v[38:39], v[34:35], v[2:3] neg_lo:[0,0,1] neg_hi:[0,0,1]
	v_pk_mul_f32 v[70:71], v[70:71], v[166:167]
	v_pk_mul_f32 v[68:69], v[24:25], v[24:25]
	v_pk_mul_f32 v[100:101], v[2:3], s[30:31] op_sel_hi:[1,0]
	v_add_f32_e32 v2, v108, v109
	v_pk_mul_f32 v[26:27], v[70:71], s[30:31] op_sel_hi:[1,0]
	v_add_f32_e32 v2, v68, v2
	v_pk_mul_f32 v[72:73], v[72:73], v[154:155]
	v_pk_mul_f32 v[70:71], v[26:27], v[26:27]
	v_add_f32_e32 v2, v69, v2
	v_pk_mul_f32 v[28:29], v[72:73], s[30:31] op_sel_hi:[1,0]
	v_add_f32_e32 v2, v70, v2
	v_pk_mul_f32 v[78:79], v[78:79], v[152:153]
	v_pk_mul_f32 v[10:11], v[38:39], v[4:5]
	v_pk_mul_f32 v[72:73], v[28:29], v[28:29]
	v_add_f32_e32 v2, v71, v2
	v_pk_fma_f32 v[106:107], v[36:37], v[34:35], v[10:11]
	v_pk_mul_f32 v[10:11], v[78:79], s[30:31] op_sel_hi:[1,0]
	v_add_f32_e32 v2, v72, v2
	v_pk_mul_f32 v[80:81], v[80:81], v[148:149]
	v_pk_mul_f32 v[78:79], v[10:11], v[10:11]
	v_add_f32_e32 v2, v73, v2
	v_pk_mul_f32 v[14:15], v[80:81], s[30:31] op_sel_hi:[1,0]
	v_add_f32_e32 v2, v78, v2
	v_pk_mul_f32 v[62:63], v[62:63], v[146:147]
	v_pk_mul_f32 v[80:81], v[14:15], v[14:15]
	v_add_f32_e32 v2, v79, v2
	v_pk_mul_f32 v[18:19], v[62:63], s[30:31] op_sel_hi:[1,0]
	v_add_f32_e32 v2, v80, v2
	v_pk_mul_f32 v[64:65], v[64:65], v[142:143]
	v_pk_mul_f32 v[62:63], v[18:19], v[18:19]
	v_add_f32_e32 v2, v81, v2
	v_pk_mul_f32 v[20:21], v[64:65], s[30:31] op_sel_hi:[1,0]
	v_add_f32_e32 v2, v62, v2
	v_pk_mul_f32 v[74:75], v[74:75], v[138:139]
	v_pk_mul_f32 v[64:65], v[20:21], v[20:21]
	v_add_f32_e32 v2, v63, v2
	v_pk_mul_f32 v[90:91], v[74:75], s[30:31] op_sel_hi:[1,0]
	v_add_f32_e32 v2, v64, v2
	v_pk_mul_f32 v[76:77], v[76:77], v[134:135]
	v_pk_mul_f32 v[74:75], v[90:91], v[90:91]
	v_add_f32_e32 v2, v65, v2
	v_pk_mul_f32 v[92:93], v[76:77], s[30:31] op_sel_hi:[1,0]
	v_add_f32_e32 v2, v74, v2
	v_pk_mul_f32 v[58:59], v[58:59], v[130:131]
	v_pk_mul_f32 v[76:77], v[92:93], v[92:93]
	v_add_f32_e32 v2, v75, v2
	v_pk_mul_f32 v[94:95], v[58:59], s[30:31] op_sel_hi:[1,0]
	v_add_f32_e32 v2, v76, v2
	v_pk_mul_f32 v[60:61], v[60:61], v[126:127]
	v_pk_mul_f32 v[58:59], v[94:95], v[94:95]
	v_add_f32_e32 v2, v77, v2
	v_pk_mul_f32 v[98:99], v[60:61], s[30:31] op_sel_hi:[1,0]
	v_add_f32_e32 v2, v58, v2
	v_pk_mul_f32 v[54:55], v[54:55], v[122:123]
	v_pk_mul_f32 v[60:61], v[98:99], v[98:99]
	v_add_f32_e32 v2, v59, v2
	v_pk_mul_f32 v[30:31], v[54:55], s[30:31] op_sel_hi:[1,0]
	v_add_f32_e32 v2, v60, v2
	v_pk_mul_f32 v[56:57], v[56:57], v[118:119]
	v_pk_mul_f32 v[54:55], v[30:31], v[30:31]
	v_add_f32_e32 v2, v61, v2
	v_pk_mul_f32 v[32:33], v[56:57], s[30:31] op_sel_hi:[1,0]
	v_add_f32_e32 v2, v54, v2
	v_pk_mul_f32 v[50:51], v[50:51], v[114:115]
	v_pk_mul_f32 v[56:57], v[32:33], v[32:33]
	v_add_f32_e32 v2, v55, v2
	v_pk_mul_f32 v[82:83], v[50:51], s[30:31] op_sel_hi:[1,0]
	v_add_f32_e32 v2, v56, v2
	v_pk_mul_f32 v[50:51], v[82:83], v[82:83]
	v_add_f32_e32 v2, v57, v2
	v_pk_mul_f32 v[84:85], v[52:53], s[30:31] op_sel_hi:[1,0]
	v_add_f32_e32 v2, v50, v2
	v_pk_mul_f32 v[52:53], v[84:85], v[84:85]
	v_add_f32_e32 v2, v51, v2
	v_pk_mul_f32 v[16:17], v[16:17], s[30:31] op_sel_hi:[1,0]
	v_add_f32_e32 v2, v52, v2
	v_lshlrev_b32_e32 v150, 3, v159
	v_pk_mul_f32 v[66:67], v[16:17], v[16:17]
	v_add_f32_e32 v2, v53, v2
	v_ashrrev_i32_e32 v151, 31, v150
	v_add_f32_e32 v50, v66, v2
	s_waitcnt vmcnt(0)
	v_max_f32_e64 v2, |v110|, |v110|
	v_max_f32_e64 v3, |v49|, |v49|
	v_lshlrev_b64 v[152:153], 1, v[150:151]
	v_max_f32_e32 v49, v3, v2
	v_lshl_add_u64 v[2:3], s[20:21], 0, v[152:153]
	v_pk_mul_f32 v[8:9], v[42:43], s[30:31] op_sel_hi:[1,0]
	s_barrier
; #define LAS __attribute__((address_space(3)))
; __device__ __forceinline__ void attn_unit(CArgs a, int layer, int unit, LAS unsigned char* lds) {
;     ...
;     u32x4 kr0, kr1, vr;
;     const int kc0 = tid, kc1 = tid + 512;
;     constexpr int NT = SEQ / 64;
;     auto gloadK = [&](int t) {
;         const bf16_t* kt = Kg + (size_t)t * 64 * 96;
;         kr0 = *(const u32x4*)(kt + kc0 * 8);
;         kr1 = *(const u32x4*)(kt + (kc1 < 768 ? kc1 : 767) * 8);
;     };
;     auto gloadV = [&](int t) { vr = *(const u32x4*)(Vg + (size_t)t * 64 * 64 + tid * 8); };
;     auto lstoreK = [&](int buf) {
;         LAS bf16_t* Kl = (LAS bf16_t*)(lds + AT_K + buf * AT_KB);
;         *(LAS u32x4*)(Kl + (kc0 / 12) * AT_KLD + (kc0 % 12) * 8) = kr0;
;         if (kc1 < 768) *(LAS u32x4*)(Kl + (kc1 / 12) * AT_KLD + (kc1 % 12) * 8) = kr1;
;     };
;     auto lstoreV = [&](int buf) {
;         LAS bf16_t* Vl = (LAS bf16_t*)(lds + AT_V + buf * AT_VB);
;         *(LAS u32x4*)(Vl + (tid >> 3) * AT_VLD + (tid & 7) * 8) = vr;
;     };
;     ...
;     gloadK(0); gloadV(0); lstoreK(0); lstoreV(0); gloadK(1); lstoreK(1);
	global_load_dwordx4 v[42:45], v[2:3], off
	v_add_u32_e32 v236, 0x200, v159
	v_min_i32_e32 v236, 0x2ff, v236
	v_lshlrev_b32_e32 v236, 4, v236
	s_add_u32 s24, s20, 0x3000
	s_addc_u32 s25, s21, 0
	global_load_dwordx4 v[224:227], v236, s[20:21]
	global_load_dwordx4 v[228:231], v152, s[24:25]
	global_load_dwordx4 v[232:235], v236, s[24:25]
	v_xor_b32_e32 v2, 1, v247
	v_cmp_lt_i32_e32 vcc, v2, v48
	v_pk_mul_f32 v[46:47], v[86:87], v[86:87]
	v_add_f32_e32 v50, v67, v50
	v_cndmask_b32_e32 v2, v247, v2, vcc
	v_lshlrev_b32_e32 v163, 2, v2
	v_lshl_add_u64 v[2:3], s[18:19], 0, v[152:153]
	global_load_dwordx4 v[2:5], v[2:3], off
	ds_bpermute_b32 v51, v163, v49
	v_add_f32_e32 v46, v46, v50
	v_add_f32_e32 v46, v47, v46
	v_xor_b32_e32 v47, 2, v247
	v_pk_mul_f32 v[40:41], v[96:97], v[96:97]
	v_cmp_lt_i32_e32 vcc, v47, v48
	v_add_f32_e32 v40, v40, v46
	s_waitcnt lgkmcnt(0)
	v_max_f32_e32 v46, v51, v51
	v_cndmask_b32_e32 v47, v247, v47, vcc
	v_max_f32_e32 v46, v49, v46
	v_lshlrev_b32_e32 v47, 2, v47
	v_pk_mul_f32 v[34:35], v[100:101], v[100:101]
	ds_bpermute_b32 v47, v47, v46
	v_add_f32_e32 v40, v41, v40
	v_pk_mul_f32 v[6:7], v[102:103], s[30:31] op_sel_hi:[1,0]
	v_add_f32_e32 v34, v34, v40
	v_pk_mul_f32 v[36:37], v[6:7], v[6:7]
	v_add_f32_e32 v34, v35, v34
	v_add_f32_e32 v34, v36, v34
	v_xor_b32_e32 v36, 4, v247
	v_cmp_lt_i32_e32 vcc, v36, v48
	s_waitcnt lgkmcnt(0)
	v_max_f32_e32 v35, v47, v47
	v_max_f32_e32 v35, v46, v35
	v_cndmask_b32_e32 v36, v247, v36, vcc
	v_lshlrev_b32_e32 v36, 2, v36
	ds_bpermute_b32 v36, v36, v35
	v_pk_mul_f32 v[38:39], v[8:9], v[8:9]
	v_add_f32_e32 v34, v37, v34
	v_pk_mul_f32 v[12:13], v[104:105], s[30:31] op_sel_hi:[1,0]
	v_add_f32_e32 v34, v38, v34
	s_waitcnt lgkmcnt(0)
	v_max_f32_e32 v36, v36, v36
	v_max_f32_e32 v35, v35, v36
	v_xor_b32_e32 v36, 8, v247
	v_cmp_lt_i32_e32 vcc, v36, v48
	v_pk_mul_f32 v[102:103], v[12:13], v[12:13]
	v_add_f32_e32 v34, v39, v34
	v_cndmask_b32_e32 v36, v247, v36, vcc
	v_lshlrev_b32_e32 v36, 2, v36
	v_pk_mul_f32 v[88:89], v[106:107], s[30:31] op_sel_hi:[1,0]
	v_add_f32_e32 v34, v102, v34
	ds_bpermute_b32 v36, v36, v35
	v_pk_mul_f32 v[104:105], v[88:89], v[88:89]
	v_add_f32_e32 v34, v103, v34
	v_add_f32_e32 v34, v104, v34
	v_add_f32_e32 v34, v105, v34
	ds_bpermute_b32 v37, v164, v34
	s_waitcnt lgkmcnt(1)
	v_max_f32_e32 v36, v36, v36
	v_max_f32_e32 v36, v35, v36
	v_xor_b32_e32 v35, 16, v247
	v_cmp_lt_i32_e32 vcc, v35, v48
	s_waitcnt lgkmcnt(0)
	v_add_f32_e32 v34, v34, v37
	s_mov_b32 s2, 0xf800000
	v_cndmask_b32_e32 v35, v247, v35, vcc
	v_lshlrev_b32_e32 v35, 2, v35
	ds_bpermute_b32 v38, v35, v36
	v_mul_f32_e32 v35, 0x4f800000, v34
	v_cmp_gt_f32_e32 vcc, s2, v34
	s_mov_b32 s3, 0x2aaaaaab
	s_movk_i32 s2, 0xd0
	v_cndmask_b32_e32 v34, v34, v35, vcc
	v_sqrt_f32_e32 v35, v34
	s_waitcnt lgkmcnt(0)
	v_max_f32_e32 v37, v38, v38
	v_max_f32_e32 v36, v36, v37
	ds_bpermute_b32 v38, v164, v36
	v_add_u32_e32 v37, -1, v35
	v_fma_f32 v39, -v37, v35, v34
	v_cmp_ge_f32_e64 s[42:43], 0, v39
	v_add_u32_e32 v39, 1, v35
	v_fma_f32 v40, -v39, v35, v34
	v_cmp_lt_f32_e64 s[44:45], 0, v40
	v_add_u32_e32 v40, 0x200, v159
	v_min_i32_e32 v41, 0x2ff, v40
	v_lshlrev_b32_e32 v154, 3, v41
	v_mul_hi_i32 v41, v159, s3
	v_lshrrev_b32_e32 v46, 31, v41
	v_ashrrev_i32_e32 v41, 1, v41
	v_add_u32_e32 v41, v41, v46
	v_mul_lo_u32 v46, v41, s2
	v_mul_lo_u32 v41, v41, 12
	v_sub_u32_e32 v41, v159, v41
	v_add_u32_e32 v46, 0, v46
	v_lshlrev_b32_e32 v41, 4, v41
	s_movk_i32 s2, 0xff
	v_add_u32_e32 v166, v46, v41
	v_cmp_lt_i32_e64 s[46:47], s2, v159
	s_movk_i32 s2, 0x100
	v_mul_hi_i32 v41, v40, s3
	v_ashrrev_i32_e32 v155, 31, v154
	s_waitcnt vmcnt(4)
	ds_write_b128 v166, v[42:45]
	v_cmp_gt_i32_e64 s[40:41], s2, v159
	v_lshrrev_b32_e32 v42, 31, v41
	v_ashrrev_i32_e32 v41, 1, v41
	s_and_saveexec_b64 s[2:3], s[40:41]
	s_cbranch_execz .LBB0_68
	v_add_u32_e32 v43, v41, v42
	s_movk_i32 s12, 0xd0
	v_mul_lo_u32 v48, v43, s12
	v_mul_lo_u32 v43, v43, 12
	v_sub_u32_e32 v43, v40, v43
	v_lshlrev_b32_e32 v43, 4, v43
	v_add3_u32 v43, 0, v48, v43
	s_waitcnt vmcnt(3)
	ds_write_b128 v43, v[224:227]
.LBB0_68:
	s_or_b64 exec, exec, s[2:3]
	v_lshrrev_b32_e32 v43, 3, v159
	v_and_b32_e32 v44, 56, v150
	v_mul_lo_u32 v43, v43, s82
	v_lshlrev_b32_e32 v44, 1, v44
	s_add_u32 s24, s20, 0x3000
	v_add3_u32 v167, 0, v43, v44
	s_addc_u32 s25, s21, 0
	s_waitcnt vmcnt(0)
	ds_write_b128 v167, v[2:5] offset:26624
	ds_write_b128 v166, v[228:231] offset:13312
	s_and_saveexec_b64 s[2:3], s[46:47]
	s_xor_b64 s[2:3], exec, s[2:3]
	s_mov_b32 s12, 0xaaaaaaab
	v_mul_hi_u32 v2, v40, s12
	v_lshrrev_b32_e32 v2, 3, v2
	s_movk_i32 s12, 0xd0
	v_mul_lo_u32 v3, v2, s12
	v_mul_lo_u32 v2, v2, 12
	v_sub_u32_e32 v2, v40, v2
	v_lshlrev_b32_e32 v2, 4, v2
	s_andn2_saveexec_b64 s[2:3], s[2:3]
	s_cbranch_execz .LBB0_72
	v_add_u32_e32 v2, v41, v42
	s_movk_i32 s12, 0xd0
	v_mul_lo_u32 v3, v2, s12
	v_mul_lo_u32 v2, v2, 12
	v_sub_u32_e32 v2, v40, v2
	v_lshlrev_b32_e32 v2, 4, v2
	v_add3_u32 v4, 0, v3, v2
	ds_write_b128 v4, v[232:235] offset:13312
; #define LAS __attribute__((address_space(3)))
; #define MFMA32(a, b, c) __builtin_amdgcn_mfma_f32_32x32x16_bf16((a), (b), (c), 0, 0, 0)
; __device__ __forceinline__ void attn_unit(CArgs a, int layer, int unit, LAS unsigned char* lds) {
;     ...
;         mref = 1.02f * sqrtf(qn2) * 9.797958971f * gm;
;     }
;     u32x4 kr0, kr1, vr;
;     const int kc0 = tid, kc1 = tid + 512;
;     constexpr int NT = SEQ / 64;
;     auto gloadK = [&](int t) {
;         const bf16_t* kt = Kg + (size_t)t * 64 * 96;
;         kr0 = *(const u32x4*)(kt + kc0 * 8);
;         kr1 = *(const u32x4*)(kt + (kc1 < 768 ? kc1 : 767) * 8);
;     };
;     auto gloadV = [&](int t) { vr = *(const u32x4*)(Vg + (size_t)t * 64 * 64 + tid * 8); };
;     auto lstoreK = [&](int buf) {
;         LAS bf16_t* Kl = (LAS bf16_t*)(lds + AT_K + buf * AT_KB);
;         *(LAS u32x4*)(Kl + (kc0 / 12) * AT_KLD + (kc0 % 12) * 8) = kr0;
;         if (kc1 < 768) *(LAS u32x4*)(Kl + (kc1 / 12) * AT_KLD + (kc1 % 12) * 8) = kr1;
;     };
;     auto lstoreV = [&](int buf) {
;         LAS bf16_t* Vl = (LAS bf16_t*)(lds + AT_V + buf * AT_VB);
;         *(LAS u32x4*)(Vl + (tid >> 3) * AT_VLD + (tid & 7) * 8) = vr;
;     };
;     f32x16 negm;
; #pragma unroll
;     for (int r = 0; r < 16; ++r) negm[r] = -mref;
;     auto qk = [&](int buf, f32x16& p0, f32x16& p1) {
;         const LAS bf16_t* Kl = (const LAS bf16_t*)(lds + AT_K + buf * AT_KB);
; #pragma unroll
;         for (int s = 0; s < 6; ++s) {
;             const bf16x8 k0 = *(const LAS bf16x8*)(Kl + r32 * AT_KLD + 16 * s + 8 * hi);
;             const bf16x8 k1 = *(const LAS bf16x8*)(Kl + (32 + r32) * AT_KLD + 16 * s + 8 * hi);
;             if (s == 0) { p0 = MFMA32(k0, qf[0], negm); p1 = MFMA32(k1, qf[0], negm); }
;             else { p0 = MFMA32(k0, qf[s], p0); p1 = MFMA32(k1, qf[s], p1); }
;         }
;     };
;     __syncthreads();
;     gloadK(0); gloadV(0); lstoreK(0); lstoreV(0); gloadK(1); lstoreK(1);
;     __syncthreads();
;     float lrun = 0.f;
;     f32x16 o0, o1, pA0, pA1, pB0, pB1;
; #pragma unroll
;     for (int r = 0; r < 16; ++r) { o0[r] = 0.f; o1[r] = 0.f; }
;     qk(0, pA0, pA1);
;     auto tile = [&](int t, f32x16& c0, f32x16& c1, f32x16& n0, f32x16& n1) {
;         const int buf = t & 1;
;         gloadK(t + 2 < NT ? t + 2 : NT - 1); gloadV(t + 1 < NT ? t + 1 : NT - 1);
.LBB0_72:
	s_or_b64 exec, exec, s[2:3]
	v_cndmask_b32_e64 v35, v35, v37, s[42:43]
	s_waitcnt lgkmcnt(3)
	v_max_f32_e32 v5, v38, v38
	v_cndmask_b32_e64 v35, v35, v39, s[44:45]
	v_max_f32_e32 v5, v36, v5
	v_mul_f32_e32 v36, 0x37800000, v35
	v_cndmask_b32_e32 v35, v35, v36, vcc
	v_mov_b32_e32 v36, 0x260
	v_cmp_class_f32_e32 vcc, v34, v36
	v_cvt_pk_bf16_f32 v114, v22, v23
	v_lshlrev_b32_e32 v4, 3, v160
	v_cndmask_b32_e32 v34, v35, v34, vcc
	v_mul_f32_e32 v22, 0xbf828f5c, v34
	v_mul_f32_e32 v22, 0x411cc471, v22
	v_mul_f32_e32 v34, v22, v5
	v_mul_u32_u24_e32 v5, 0xd0, v161
	v_lshlrev_b32_e32 v4, 1, v4
	v_add3_u32 v168, 0, v5, v4
	v_cvt_pk_bf16_f32 v115, v24, v25
	s_waitcnt lgkmcnt(0)
	s_barrier
	ds_read_b128 v[22:25], v168
	v_cvt_pk_bf16_f32 v116, v26, v27
	v_cvt_pk_bf16_f32 v117, v28, v29
	v_mov_b32_e32 v35, v34
	v_mov_b32_e32 v36, v34
	v_mov_b32_e32 v37, v34
	v_mov_b32_e32 v38, v34
	v_mov_b32_e32 v39, v34
	v_mov_b32_e32 v40, v34
	v_mov_b32_e32 v41, v34
	v_mov_b32_e32 v42, v34
	v_mov_b32_e32 v43, v34
	v_mov_b32_e32 v44, v34
	v_mov_b32_e32 v45, v34
	v_mov_b32_e32 v46, v34
	v_mov_b32_e32 v47, v34
	v_mov_b32_e32 v48, v34
	v_mov_b32_e32 v49, v34
	ds_read_b128 v[26:29], v168 offset:32
	v_cvt_pk_bf16_f32 v118, v10, v11
	s_waitcnt lgkmcnt(1)
	v_mfma_f32_32x32x16_bf16 v[50:65], v[22:25], v[114:117], v[34:49]
	ds_read_b128 v[22:25], v168 offset:6656
	ds_read_b128 v[102:105], v168 offset:6688
	v_cvt_pk_bf16_f32 v119, v14, v15
	v_cvt_pk_bf16_f32 v120, v18, v19
	v_cvt_pk_bf16_f32 v121, v20, v21
	ds_read_b128 v[18:21], v168 offset:64
	v_cvt_pk_bf16_f32 v122, v90, v91
	v_cvt_pk_bf16_f32 v123, v92, v93
	s_waitcnt lgkmcnt(2)
	v_mfma_f32_32x32x16_bf16 v[66:81], v[22:25], v[114:117], v[34:49]
	v_cvt_pk_bf16_f32 v124, v94, v95
	v_cvt_pk_bf16_f32 v125, v98, v99
	ds_read_b128 v[22:25], v168 offset:96
	v_cvt_pk_bf16_f32 v126, v30, v31
	v_cvt_pk_bf16_f32 v127, v32, v33
	v_cvt_pk_bf16_f32 v128, v82, v83
	v_cvt_pk_bf16_f32 v129, v84, v85
	v_mfma_f32_32x32x16_bf16 v[50:65], v[26:29], v[118:121], v[50:65]
	v_cvt_pk_bf16_f32 v130, v16, v17
	v_cvt_pk_bf16_f32 v131, v86, v87
	v_cvt_pk_bf16_f32 v132, v96, v97
	v_cvt_pk_bf16_f32 v133, v100, v101
	v_cvt_pk_bf16_f32 v134, v6, v7
	v_cvt_pk_bf16_f32 v135, v8, v9
	v_cvt_pk_bf16_f32 v136, v12, v13
	s_waitcnt lgkmcnt(2)
	v_mfma_f32_32x32x16_bf16 v[66:81], v[102:105], v[118:121], v[66:81]
	v_cvt_pk_bf16_f32 v137, v88, v89
	v_lshlrev_b32_e32 v169, 2, v160
	v_lshrrev_b32_e32 v8, 2, v159
	v_and_or_b32 v8, v8, 3, v169
	v_and_b32_e32 v9, 16, v159
	v_lshlrev_b32_e32 v10, 3, v0
	s_add_u32 s2, s60, s22
	s_waitcnt lgkmcnt(1)
	v_mfma_f32_32x32x16_bf16 v[50:65], v[18:21], v[122:125], v[50:65]
	ds_read_b128 v[18:21], v168 offset:6720
	ds_read_b128 v[26:29], v168 offset:6752
	ds_read_b128 v[14:17], v168 offset:160
	ds_read_b128 v[4:7], v168 offset:6816
	v_mad_u32_u24 v8, v8, s82, 0
	v_lshlrev_b32_e32 v9, 1, v9
	v_and_b32_e32 v10, 24, v10
	s_addc_u32 s3, s61, s23
	s_waitcnt lgkmcnt(3)
	v_mfma_f32_32x32x16_bf16 v[66:81], v[18:21], v[122:125], v[66:81]
	ds_read_b128 v[18:21], v168 offset:128
	v_add3_u32 v170, v8, v9, v10
	v_add_u32_e32 v3, 0, v3
	v_lshl_add_u64 v[8:9], v[150:151], 1, s[2:3]
	s_mov_b64 s[2:3], 0x17a02000
	v_mov_b32_e32 v172, 0
	v_lshl_add_u64 v[156:157], v[8:9], 0, s[2:3]
	v_mfma_f32_32x32x16_bf16 v[50:65], v[22:25], v[126:129], v[50:65]
	s_mov_b32 s13, -2
	v_add_u32_e32 v171, v3, v2
	v_mov_b32_e32 v2, 0
	v_mov_b32_e32 v3, v172
	v_mov_b32_e32 v8, v172
	v_mov_b32_e32 v9, v172
	v_mov_b32_e32 v10, v172
	s_waitcnt lgkmcnt(0)
	v_mfma_f32_32x32x16_bf16 v[50:65], v[18:21], v[130:133], v[50:65]
	ds_read_b128 v[18:21], v168 offset:6784
	v_mov_b32_e32 v11, v172
	v_mov_b32_e32 v12, v172
	v_mov_b32_e32 v13, v172
	v_mov_b32_e32 v22, v172
	v_mov_b32_e32 v23, v172
	v_mov_b32_e32 v24, v172
	v_mfma_f32_32x32x16_bf16 v[66:81], v[26:29], v[126:129], v[66:81]
	v_mov_b32_e32 v25, v172
	v_mov_b32_e32 v26, v172
	v_mov_b32_e32 v27, v172
	v_mov_b32_e32 v28, v172
	v_mov_b32_e32 v29, v172
	v_mov_b32_e32 v30, v172
	v_mov_b32_e32 v31, v172
	s_waitcnt lgkmcnt(0)
	v_mfma_f32_32x32x16_bf16 v[66:81], v[18:21], v[130:133], v[66:81]
	v_mov_b32_e32 v18, 0
	v_mov_b32_e32 v19, v172
	v_mov_b32_e32 v20, v172
	v_mov_b32_e32 v21, v172
	v_mov_b32_e32 v32, v172
	v_mov_b32_e32 v33, v172
	v_mfma_f32_32x32x16_bf16 v[50:65], v[14:17], v[134:137], v[50:65]
	v_mov_b32_e32 v14, v172
	v_mov_b32_e32 v15, v172
	v_mov_b32_e32 v16, v172
	v_mov_b32_e32 v17, v172
	v_mfma_f32_32x32x16_bf16 v[66:81], v[4:7], v[134:137], v[66:81]
	v_mov_b32_e32 v4, v172
	v_mov_b32_e32 v5, v172
	v_mov_b32_e32 v6, v172
	v_mov_b32_e32 v7, v172
	v_lshlrev_b32_e32 v175, 1, v154
	s_add_u32 s2, s20, 0x6000
	s_addc_u32 s3, s21, 0
	s_add_u32 s24, s18, 0x2000
	s_addc_u32 s25, s19, 0
	global_load_dwordx4 v[224:227], v152, s[2:3]
	global_load_dwordx4 v[228:231], v175, s[2:3]
	global_load_dwordx4 v[232:235], v152, s[24:25]
	s_mov_b32 s13, 0
; __device__ __forceinline__ void attn_unit(CArgs a, int layer, int unit, LAS unsigned char* lds) {
;     ...
;     auto tile = [&](int t, f32x16& c0, f32x16& c1, f32x16& n0, f32x16& n1) {
;         const int buf = t & 1;
;         gloadK(t + 2 < NT ? t + 2 : NT - 1); gloadV(t + 1 < NT ? t + 1 : NT - 1);
;         const LAS bf16_t* Vl = (const LAS bf16_t*)(lds + AT_V + buf * AT_VB);
;         if (t + 1 < NT) qk(buf ^ 1, n0, n1);
;         f32x16 p0, p1;
;         float rs = 0.f;
; #pragma unroll
;         for (int r = 0; r < 16; ++r) { p0[r] = __builtin_amdgcn_exp2f(c0[r]); p1[r] = __builtin_amdgcn_exp2f(c1[r]); rs += p0[r] + p1[r]; }
;         lrun += rs;
;         bf16x8 pf[4];
; #pragma unroll
;         for (int s = 0; s < 2; ++s) {
;             u32x4 w0, w1;
;             w0.x = cvt_pk_bf16(p0[8 * s], p0[8 * s + 1]); w0.y = cvt_pk_bf16(p0[8 * s + 2], p0[8 * s + 3]); w0.z = cvt_pk_bf16(p0[8 * s + 4], p0[8 * s + 5]); w0.w = cvt_pk_bf16(p0[8 * s + 6], p0[8 * s + 7]);
;             w1.x = cvt_pk_bf16(p1[8 * s], p1[8 * s + 1]); w1.y = cvt_pk_bf16(p1[8 * s + 2], p1[8 * s + 3]); w1.z = cvt_pk_bf16(p1[8 * s + 4], p1[8 * s + 5]); w1.w = cvt_pk_bf16(p1[8 * s + 6], p1[8 * s + 7]);
;             pf[s] = __builtin_bit_cast(bf16x8, w0); pf[2 + s] = __builtin_bit_cast(bf16x8, w1);
;         }
; #pragma unroll
;         for (int i = 0; i < 12; ++i) { __builtin_amdgcn_sched_group_barrier(0x008, 1, 0); __builtin_amdgcn_sched_group_barrier(0x002, 9, 0); }
; #pragma unroll
;         for (int s4 = 0; s4 < 4; ++s4) {
;             const int kb = 32 * (s4 >> 1) + 16 * (s4 & 1) + 4 * hi;
;             const LAS bf16_t* vrow = Vl + (kb - 4 * hi + 4 * hi + ((lane & 15) >> 2)) * AT_VLD + 16 * ((lane >> 4) & 1) + 4 * (lane & 3);
;             const v4i16_t a0 = __builtin_amdgcn_ds_read_tr16_b64_v4i16((LAS v4i16_t*)(vrow)), a1 = __builtin_amdgcn_ds_read_tr16_b64_v4i16((LAS v4i16_t*)(vrow + 8 * AT_VLD));
;             const v4i16_t c0 = __builtin_amdgcn_ds_read_tr16_b64_v4i16((LAS v4i16_t*)(vrow + 32)), c1 = __builtin_amdgcn_ds_read_tr16_b64_v4i16((LAS v4i16_t*)(vrow + 8 * AT_VLD + 32));
;             const bf16x8 v0 = __builtin_shufflevector(a0, a1, 0, 1, 2, 3, 4, 5, 6, 7), v1 = __builtin_shufflevector(c0, c1, 0, 1, 2, 3, 4, 5, 6, 7);
;             o0 = MFMA32(pf[s4], v0, o0);
;             o1 = MFMA32(pf[s4], v1, o1);
;         }
;         lstoreK(buf); lstoreV(buf ^ 1);
.Lattn_loop:
	s_add_i32 s12, s13, 3
	s_min_u32 s12, s12, 31
	s_mul_i32 s12, s12, 0x3000
	s_add_u32 s2, s20, s12
	s_addc_u32 s3, s21, 0
	s_add_i32 s12, s13, 2
	s_min_u32 s12, s12, 31
	s_lshl_b32 s12, s12, 13
	s_add_u32 s24, s18, s12
	s_addc_u32 s25, s19, 0
	global_load_dwordx4 v[200:203], v152, s[2:3]
	global_load_dwordx4 v[204:207], v175, s[2:3]
	global_load_dwordx4 v[208:211], v152, s[24:25]
	ds_read_b128 v[138:141], v168 offset:13312
	ds_read_b128 v[142:145], v168 offset:19968
	ds_read_b128 v[146:149], v168 offset:13344
	ds_read_b64_tr_b16 v[212:213], v170 offset:26624
	ds_read_b64_tr_b16 v[214:215], v170 offset:27776
	ds_read_b64_tr_b16 v[216:217], v170 offset:26688
	ds_read_b64_tr_b16 v[218:219], v170 offset:27840
	v_exp_f32_e32 v192, v50
	v_exp_f32_e32 v193, v51
	v_exp_f32_e32 v194, v52
	v_exp_f32_e32 v195, v53
	v_exp_f32_e32 v196, v54
	v_exp_f32_e32 v197, v55
	v_exp_f32_e32 v198, v56
	v_exp_f32_e32 v199, v57
	s_waitcnt lgkmcnt(6)
	v_mfma_f32_32x32x16_bf16 v[98:113], v[138:141], v[114:117], v[34:49]
	ds_read_b128 v[138:141], v168 offset:20000
	v_add_f32_e32 v173, v192, v193
	v_add_f32_e32 v174, v194, v195
	v_add_f32_e32 v173, v173, v196
	v_add_f32_e32 v174, v174, v197
	v_add_f32_e32 v173, v173, v198
	v_add_f32_e32 v174, v174, v199
	s_waitcnt lgkmcnt(6)
	v_mfma_f32_32x32x16_bf16 v[82:97], v[142:145], v[114:117], v[34:49]
	ds_read_b128 v[142:145], v168 offset:13376
	v_cvt_pk_bf16_f32 v176, v192, v193
	v_cvt_pk_bf16_f32 v177, v194, v195
	v_cvt_pk_bf16_f32 v178, v196, v197
	v_cvt_pk_bf16_f32 v179, v198, v199
	s_waitcnt lgkmcnt(6)
	v_mfma_f32_32x32x16_bf16 v[98:113], v[146:149], v[118:121], v[98:113]
	ds_read_b128 v[146:149], v168 offset:20032
	v_exp_f32_e32 v192, v58
	v_exp_f32_e32 v193, v59
	v_exp_f32_e32 v194, v60
	v_exp_f32_e32 v195, v61
	v_exp_f32_e32 v196, v62
	v_exp_f32_e32 v197, v63
	v_exp_f32_e32 v198, v64
	v_exp_f32_e32 v199, v65
	s_waitcnt lgkmcnt(5)
	v_mfma_f32_32x32x16_bf16 v[2:17], v[176:179], v[212:215], v[2:17]
	ds_read_b64_tr_b16 v[220:221], v170 offset:28928
	ds_read_b64_tr_b16 v[222:223], v170 offset:30080
	v_add_f32_e32 v173, v173, v192
	v_add_f32_e32 v174, v174, v193
	v_add_f32_e32 v173, v173, v194
	v_add_f32_e32 v174, v174, v195
	v_add_f32_e32 v173, v173, v196
	v_add_f32_e32 v174, v174, v197
	v_add_f32_e32 v173, v173, v198
	v_add_f32_e32 v174, v174, v199
	s_waitcnt lgkmcnt(5)
	v_mfma_f32_32x32x16_bf16 v[18:33], v[176:179], v[216:219], v[18:33]
	ds_read_b64_tr_b16 v[236:237], v170 offset:28992
	ds_read_b64_tr_b16 v[238:239], v170 offset:30144
	v_cvt_pk_bf16_f32 v180, v192, v193
	v_cvt_pk_bf16_f32 v181, v194, v195
	v_cvt_pk_bf16_f32 v182, v196, v197
	v_cvt_pk_bf16_f32 v183, v198, v199
	s_waitcnt lgkmcnt(6)
	v_mfma_f32_32x32x16_bf16 v[82:97], v[138:141], v[118:121], v[82:97]
	ds_read_b128 v[138:141], v168 offset:13408
	s_waitcnt lgkmcnt(6)
	v_mfma_f32_32x32x16_bf16 v[98:113], v[142:145], v[122:125], v[98:113]
	ds_read_b128 v[142:145], v168 offset:20064
	s_waitcnt lgkmcnt(6)
	v_mfma_f32_32x32x16_bf16 v[82:97], v[146:149], v[122:125], v[82:97]
	ds_read_b128 v[146:149], v168 offset:13440
	v_exp_f32_e32 v192, v66
	v_exp_f32_e32 v193, v67
	v_exp_f32_e32 v194, v68
	v_exp_f32_e32 v195, v69
	v_exp_f32_e32 v196, v70
	v_exp_f32_e32 v197, v71
	v_exp_f32_e32 v198, v72
	v_exp_f32_e32 v199, v73
	s_waitcnt lgkmcnt(5)
	v_mfma_f32_32x32x16_bf16 v[2:17], v[180:183], v[220:223], v[2:17]
	ds_read_b64_tr_b16 v[212:213], v170 offset:31232
	ds_read_b64_tr_b16 v[214:215], v170 offset:32384
	v_add_f32_e32 v173, v173, v192
	v_add_f32_e32 v174, v174, v193
	v_add_f32_e32 v173, v173, v194
	v_add_f32_e32 v174, v174, v195
	v_add_f32_e32 v173, v173, v196
	v_add_f32_e32 v174, v174, v197
	v_add_f32_e32 v173, v173, v198
	v_add_f32_e32 v174, v174, v199
	s_waitcnt lgkmcnt(5)
	v_mfma_f32_32x32x16_bf16 v[18:33], v[180:183], v[236:239], v[18:33]
	ds_read_b64_tr_b16 v[216:217], v170 offset:31296
	ds_read_b64_tr_b16 v[218:219], v170 offset:32448
	v_cvt_pk_bf16_f32 v184, v192, v193
	v_cvt_pk_bf16_f32 v185, v194, v195
	v_cvt_pk_bf16_f32 v186, v196, v197
	v_cvt_pk_bf16_f32 v187, v198, v199
	s_waitcnt lgkmcnt(6)
	v_mfma_f32_32x32x16_bf16 v[98:113], v[138:141], v[126:129], v[98:113]
	ds_read_b128 v[138:141], v168 offset:20096
	s_waitcnt lgkmcnt(6)
	v_mfma_f32_32x32x16_bf16 v[82:97], v[142:145], v[126:129], v[82:97]
	ds_read_b128 v[142:145], v168 offset:13472
	s_waitcnt lgkmcnt(6)
	v_mfma_f32_32x32x16_bf16 v[98:113], v[146:149], v[130:133], v[98:113]
	ds_read_b128 v[146:149], v168 offset:20128
	v_exp_f32_e32 v192, v74
	v_exp_f32_e32 v193, v75
	v_exp_f32_e32 v194, v76
	v_exp_f32_e32 v195, v77
	v_exp_f32_e32 v196, v78
	v_exp_f32_e32 v197, v79
	v_exp_f32_e32 v198, v80
	v_exp_f32_e32 v199, v81
	s_waitcnt lgkmcnt(5)
	v_mfma_f32_32x32x16_bf16 v[2:17], v[184:187], v[212:215], v[2:17]
	ds_read_b64_tr_b16 v[220:221], v170 offset:33536
	ds_read_b64_tr_b16 v[222:223], v170 offset:34688
	v_add_f32_e32 v173, v173, v192
	v_add_f32_e32 v174, v174, v193
	v_add_f32_e32 v173, v173, v194
	v_add_f32_e32 v174, v174, v195
	v_add_f32_e32 v173, v173, v196
	v_add_f32_e32 v174, v174, v197
	v_add_f32_e32 v173, v173, v198
	v_add_f32_e32 v174, v174, v199
	s_waitcnt lgkmcnt(5)
	v_mfma_f32_32x32x16_bf16 v[18:33], v[184:187], v[216:219], v[18:33]
	ds_read_b64_tr_b16 v[236:237], v170 offset:33600
	ds_read_b64_tr_b16 v[238:239], v170 offset:34752
	v_cvt_pk_bf16_f32 v188, v192, v193
	v_cvt_pk_bf16_f32 v189, v194, v195
	v_cvt_pk_bf16_f32 v190, v196, v197
	v_cvt_pk_bf16_f32 v191, v198, v199
	s_waitcnt lgkmcnt(6)
	v_mfma_f32_32x32x16_bf16 v[82:97], v[138:141], v[130:133], v[82:97]
	s_waitcnt lgkmcnt(5)
	v_mfma_f32_32x32x16_bf16 v[98:113], v[142:145], v[134:137], v[98:113]
	s_waitcnt lgkmcnt(4)
	v_mfma_f32_32x32x16_bf16 v[82:97], v[146:149], v[134:137], v[82:97]
	v_add_f32_e32 v172, v172, v173
	v_add_f32_e32 v172, v172, v174
	s_waitcnt lgkmcnt(2)
	v_mfma_f32_32x32x16_bf16 v[2:17], v[188:191], v[220:223], v[2:17]
	s_waitcnt vmcnt(3)
	ds_write_b128 v166, v[224:227]
	ds_write_b128 v167, v[232:235] offset:35840
	s_waitcnt lgkmcnt(2)
	v_mfma_f32_32x32x16_bf16 v[18:33], v[188:191], v[236:239], v[18:33]
	s_and_b64 vcc, exec, s[40:41]
	s_cbranch_vccz .Lattn_nok1_a
	ds_write_b128 v171, v[228:231]
; __device__ __forceinline__ void attn_unit(CArgs a, int layer, int unit, LAS unsigned char* lds) {
;     ...
;     auto tile = [&](int t, f32x16& c0, f32x16& c1, f32x16& n0, f32x16& n1) {
;         const int buf = t & 1;
;         gloadK(t + 2 < NT ? t + 2 : NT - 1); gloadV(t + 1 < NT ? t + 1 : NT - 1);
;         const LAS bf16_t* Vl = (const LAS bf16_t*)(lds + AT_V + buf * AT_VB);
;         if (t + 1 < NT) qk(buf ^ 1, n0, n1);
;         f32x16 p0, p1;
;         float rs = 0.f;
; #pragma unroll
;         for (int r = 0; r < 16; ++r) { p0[r] = __builtin_amdgcn_exp2f(c0[r]); p1[r] = __builtin_amdgcn_exp2f(c1[r]); rs += p0[r] + p1[r]; }
;         lrun += rs;
;         bf16x8 pf[4];
; #pragma unroll
;         for (int s = 0; s < 2; ++s) {
;             u32x4 w0, w1;
;             w0.x = cvt_pk_bf16(p0[8 * s], p0[8 * s + 1]); w0.y = cvt_pk_bf16(p0[8 * s + 2], p0[8 * s + 3]); w0.z = cvt_pk_bf16(p0[8 * s + 4], p0[8 * s + 5]); w0.w = cvt_pk_bf16(p0[8 * s + 6], p0[8 * s + 7]);
;             w1.x = cvt_pk_bf16(p1[8 * s], p1[8 * s + 1]); w1.y = cvt_pk_bf16(p1[8 * s + 2], p1[8 * s + 3]); w1.z = cvt_pk_bf16(p1[8 * s + 4], p1[8 * s + 5]); w1.w = cvt_pk_bf16(p1[8 * s + 6], p1[8 * s + 7]);
;             pf[s] = __builtin_bit_cast(bf16x8, w0); pf[2 + s] = __builtin_bit_cast(bf16x8, w1);
;         }
; #pragma unroll
;         for (int i = 0; i < 12; ++i) { __builtin_amdgcn_sched_group_barrier(0x008, 1, 0); __builtin_amdgcn_sched_group_barrier(0x002, 9, 0); }
; #pragma unroll
;         for (int s4 = 0; s4 < 4; ++s4) {
;             const int kb = 32 * (s4 >> 1) + 16 * (s4 & 1) + 4 * hi;
;             const LAS bf16_t* vrow = Vl + (kb - 4 * hi + 4 * hi + ((lane & 15) >> 2)) * AT_VLD + 16 * ((lane >> 4) & 1) + 4 * (lane & 3);
;             const v4i16_t a0 = __builtin_amdgcn_ds_read_tr16_b64_v4i16((LAS v4i16_t*)(vrow)), a1 = __builtin_amdgcn_ds_read_tr16_b64_v4i16((LAS v4i16_t*)(vrow + 8 * AT_VLD));
;             const v4i16_t c0 = __builtin_amdgcn_ds_read_tr16_b64_v4i16((LAS v4i16_t*)(vrow + 32)), c1 = __builtin_amdgcn_ds_read_tr16_b64_v4i16((LAS v4i16_t*)(vrow + 8 * AT_VLD + 32));
;             const bf16x8 v0 = __builtin_shufflevector(a0, a1, 0, 1, 2, 3, 4, 5, 6, 7), v1 = __builtin_shufflevector(c0, c1, 0, 1, 2, 3, 4, 5, 6, 7);
;             o0 = MFMA32(pf[s4], v0, o0);
;             o1 = MFMA32(pf[s4], v1, o1);
;         }
;         lstoreK(buf); lstoreV(buf ^ 1);
.Lattn_nok1_a:
	s_waitcnt lgkmcnt(0)
	s_barrier
	s_add_i32 s12, s13, 4
	s_min_u32 s12, s12, 31
	s_mul_i32 s12, s12, 0x3000
	s_add_u32 s2, s20, s12
	s_addc_u32 s3, s21, 0
	s_add_i32 s12, s13, 3
	s_min_u32 s12, s12, 31
	s_lshl_b32 s12, s12, 13
	s_add_u32 s24, s18, s12
	s_addc_u32 s25, s19, 0
	global_load_dwordx4 v[224:227], v152, s[2:3]
	global_load_dwordx4 v[228:231], v175, s[2:3]
	global_load_dwordx4 v[232:235], v152, s[24:25]
	ds_read_b128 v[138:141], v168 offset:0
	ds_read_b128 v[142:145], v168 offset:6656
	ds_read_b128 v[146:149], v168 offset:32
	ds_read_b64_tr_b16 v[212:213], v170 offset:35840
	ds_read_b64_tr_b16 v[214:215], v170 offset:36992
	ds_read_b64_tr_b16 v[216:217], v170 offset:35904
	ds_read_b64_tr_b16 v[218:219], v170 offset:37056
	v_exp_f32_e32 v192, v98
	v_exp_f32_e32 v193, v99
	v_exp_f32_e32 v194, v100
	v_exp_f32_e32 v195, v101
	v_exp_f32_e32 v196, v102
	v_exp_f32_e32 v197, v103
	v_exp_f32_e32 v198, v104
	v_exp_f32_e32 v199, v105
	s_waitcnt lgkmcnt(6)
	v_mfma_f32_32x32x16_bf16 v[50:65], v[138:141], v[114:117], v[34:49]
	ds_read_b128 v[138:141], v168 offset:6688
	v_add_f32_e32 v173, v192, v193
	v_add_f32_e32 v174, v194, v195
	v_add_f32_e32 v173, v173, v196
	v_add_f32_e32 v174, v174, v197
	v_add_f32_e32 v173, v173, v198
	v_add_f32_e32 v174, v174, v199
	s_waitcnt lgkmcnt(6)
	v_mfma_f32_32x32x16_bf16 v[66:81], v[142:145], v[114:117], v[34:49]
	ds_read_b128 v[142:145], v168 offset:64
	v_cvt_pk_bf16_f32 v176, v192, v193
	v_cvt_pk_bf16_f32 v177, v194, v195
	v_cvt_pk_bf16_f32 v178, v196, v197
	v_cvt_pk_bf16_f32 v179, v198, v199
	s_waitcnt lgkmcnt(6)
	v_mfma_f32_32x32x16_bf16 v[50:65], v[146:149], v[118:121], v[50:65]
	ds_read_b128 v[146:149], v168 offset:6720
	v_exp_f32_e32 v192, v106
	v_exp_f32_e32 v193, v107
	v_exp_f32_e32 v194, v108
	v_exp_f32_e32 v195, v109
	v_exp_f32_e32 v196, v110
	v_exp_f32_e32 v197, v111
	v_exp_f32_e32 v198, v112
	v_exp_f32_e32 v199, v113
	s_waitcnt lgkmcnt(5)
	v_mfma_f32_32x32x16_bf16 v[2:17], v[176:179], v[212:215], v[2:17]
	ds_read_b64_tr_b16 v[220:221], v170 offset:38144
	ds_read_b64_tr_b16 v[222:223], v170 offset:39296
	v_add_f32_e32 v173, v173, v192
	v_add_f32_e32 v174, v174, v193
	v_add_f32_e32 v173, v173, v194
	v_add_f32_e32 v174, v174, v195
	v_add_f32_e32 v173, v173, v196
	v_add_f32_e32 v174, v174, v197
	v_add_f32_e32 v173, v173, v198
	v_add_f32_e32 v174, v174, v199
	s_waitcnt lgkmcnt(5)
	v_mfma_f32_32x32x16_bf16 v[18:33], v[176:179], v[216:219], v[18:33]
	ds_read_b64_tr_b16 v[236:237], v170 offset:38208
	ds_read_b64_tr_b16 v[238:239], v170 offset:39360
	v_cvt_pk_bf16_f32 v180, v192, v193
	v_cvt_pk_bf16_f32 v181, v194, v195
	v_cvt_pk_bf16_f32 v182, v196, v197
	v_cvt_pk_bf16_f32 v183, v198, v199
	s_waitcnt lgkmcnt(6)
	v_mfma_f32_32x32x16_bf16 v[66:81], v[138:141], v[118:121], v[66:81]
	ds_read_b128 v[138:141], v168 offset:96
	s_waitcnt lgkmcnt(6)
	v_mfma_f32_32x32x16_bf16 v[50:65], v[142:145], v[122:125], v[50:65]
	ds_read_b128 v[142:145], v168 offset:6752
	s_waitcnt lgkmcnt(6)
	v_mfma_f32_32x32x16_bf16 v[66:81], v[146:149], v[122:125], v[66:81]
	ds_read_b128 v[146:149], v168 offset:128
	v_exp_f32_e32 v192, v82
	v_exp_f32_e32 v193, v83
	v_exp_f32_e32 v194, v84
	v_exp_f32_e32 v195, v85
	v_exp_f32_e32 v196, v86
	v_exp_f32_e32 v197, v87
	v_exp_f32_e32 v198, v88
	v_exp_f32_e32 v199, v89
	s_waitcnt lgkmcnt(5)
	v_mfma_f32_32x32x16_bf16 v[2:17], v[180:183], v[220:223], v[2:17]
	ds_read_b64_tr_b16 v[212:213], v170 offset:40448
	ds_read_b64_tr_b16 v[214:215], v170 offset:41600
	v_add_f32_e32 v173, v173, v192
	v_add_f32_e32 v174, v174, v193
	v_add_f32_e32 v173, v173, v194
	v_add_f32_e32 v174, v174, v195
	v_add_f32_e32 v173, v173, v196
	v_add_f32_e32 v174, v174, v197
	v_add_f32_e32 v173, v173, v198
	v_add_f32_e32 v174, v174, v199
	s_waitcnt lgkmcnt(5)
	v_mfma_f32_32x32x16_bf16 v[18:33], v[180:183], v[236:239], v[18:33]
	ds_read_b64_tr_b16 v[216:217], v170 offset:40512
	ds_read_b64_tr_b16 v[218:219], v170 offset:41664
	v_cvt_pk_bf16_f32 v184, v192, v193
	v_cvt_pk_bf16_f32 v185, v194, v195
	v_cvt_pk_bf16_f32 v186, v196, v197
	v_cvt_pk_bf16_f32 v187, v198, v199
	s_waitcnt lgkmcnt(6)
	v_mfma_f32_32x32x16_bf16 v[50:65], v[138:141], v[126:129], v[50:65]
	ds_read_b128 v[138:141], v168 offset:6784
	s_waitcnt lgkmcnt(6)
	v_mfma_f32_32x32x16_bf16 v[66:81], v[142:145], v[126:129], v[66:81]
	ds_read_b128 v[142:145], v168 offset:160
	s_waitcnt lgkmcnt(6)
	v_mfma_f32_32x32x16_bf16 v[50:65], v[146:149], v[130:133], v[50:65]
	ds_read_b128 v[146:149], v168 offset:6816
	v_exp_f32_e32 v192, v90
	v_exp_f32_e32 v193, v91
	v_exp_f32_e32 v194, v92
	v_exp_f32_e32 v195, v93
	v_exp_f32_e32 v196, v94
	v_exp_f32_e32 v197, v95
	v_exp_f32_e32 v198, v96
	v_exp_f32_e32 v199, v97
	s_waitcnt lgkmcnt(5)
	v_mfma_f32_32x32x16_bf16 v[2:17], v[184:187], v[212:215], v[2:17]
	ds_read_b64_tr_b16 v[220:221], v170 offset:42752
	ds_read_b64_tr_b16 v[222:223], v170 offset:43904
	v_add_f32_e32 v173, v173, v192
	v_add_f32_e32 v174, v174, v193
	v_add_f32_e32 v173, v173, v194
	v_add_f32_e32 v174, v174, v195
	v_add_f32_e32 v173, v173, v196
	v_add_f32_e32 v174, v174, v197
	v_add_f32_e32 v173, v173, v198
	v_add_f32_e32 v174, v174, v199
	s_waitcnt lgkmcnt(5)
	v_mfma_f32_32x32x16_bf16 v[18:33], v[184:187], v[216:219], v[18:33]
	ds_read_b64_tr_b16 v[236:237], v170 offset:42816
	ds_read_b64_tr_b16 v[238:239], v170 offset:43968
	v_cvt_pk_bf16_f32 v188, v192, v193
	v_cvt_pk_bf16_f32 v189, v194, v195
	v_cvt_pk_bf16_f32 v190, v196, v197
	v_cvt_pk_bf16_f32 v191, v198, v199
	s_waitcnt lgkmcnt(6)
	v_mfma_f32_32x32x16_bf16 v[66:81], v[138:141], v[130:133], v[66:81]
	s_waitcnt lgkmcnt(5)
	v_mfma_f32_32x32x16_bf16 v[50:65], v[142:145], v[134:137], v[50:65]
	s_waitcnt lgkmcnt(4)
	v_mfma_f32_32x32x16_bf16 v[66:81], v[146:149], v[134:137], v[66:81]
	v_add_f32_e32 v172, v172, v173
	v_add_f32_e32 v172, v172, v174
	s_waitcnt lgkmcnt(2)
	v_mfma_f32_32x32x16_bf16 v[2:17], v[188:191], v[220:223], v[2:17]
	s_waitcnt vmcnt(3)
	ds_write_b128 v166, v[200:203] offset:13312
	ds_write_b128 v167, v[208:211] offset:26624
	s_waitcnt lgkmcnt(2)
	v_mfma_f32_32x32x16_bf16 v[18:33], v[188:191], v[236:239], v[18:33]
	s_and_b64 vcc, exec, s[40:41]
	s_cbranch_vccz .Lattn_nok1_b
	ds_write_b128 v171, v[204:207] offset:13312
; __device__ __forceinline__ void attn_unit(CArgs a, int layer, int unit, LAS unsigned char* lds) {
;     ...
;     auto tile = [&](int t, f32x16& c0, f32x16& c1, f32x16& n0, f32x16& n1) {
;         const int buf = t & 1;
;         gloadK(t + 2 < NT ? t + 2 : NT - 1); gloadV(t + 1 < NT ? t + 1 : NT - 1);
;         const LAS bf16_t* Vl = (const LAS bf16_t*)(lds + AT_V + buf * AT_VB);
;         if (t + 1 < NT) qk(buf ^ 1, n0, n1);
;         f32x16 p0, p1;
;         float rs = 0.f;
; #pragma unroll
;         for (int r = 0; r < 16; ++r) { p0[r] = __builtin_amdgcn_exp2f(c0[r]); p1[r] = __builtin_amdgcn_exp2f(c1[r]); rs += p0[r] + p1[r]; }
;         lrun += rs;
;         bf16x8 pf[4];
; #pragma unroll
;         for (int s = 0; s < 2; ++s) {
;             u32x4 w0, w1;
;             w0.x = cvt_pk_bf16(p0[8 * s], p0[8 * s + 1]); w0.y = cvt_pk_bf16(p0[8 * s + 2], p0[8 * s + 3]); w0.z = cvt_pk_bf16(p0[8 * s + 4], p0[8 * s + 5]); w0.w = cvt_pk_bf16(p0[8 * s + 6], p0[8 * s + 7]);
;             w1.x = cvt_pk_bf16(p1[8 * s], p1[8 * s + 1]); w1.y = cvt_pk_bf16(p1[8 * s + 2], p1[8 * s + 3]); w1.z = cvt_pk_bf16(p1[8 * s + 4], p1[8 * s + 5]); w1.w = cvt_pk_bf16(p1[8 * s + 6], p1[8 * s + 7]);
;             pf[s] = __builtin_bit_cast(bf16x8, w0); pf[2 + s] = __builtin_bit_cast(bf16x8, w1);
;         }
; #pragma unroll
;         for (int i = 0; i < 12; ++i) { __builtin_amdgcn_sched_group_barrier(0x008, 1, 0); __builtin_amdgcn_sched_group_barrier(0x002, 9, 0); }
; #pragma unroll
;         for (int s4 = 0; s4 < 4; ++s4) {
;             const int kb = 32 * (s4 >> 1) + 16 * (s4 & 1) + 4 * hi;
;             const LAS bf16_t* vrow = Vl + (kb - 4 * hi + 4 * hi + ((lane & 15) >> 2)) * AT_VLD + 16 * ((lane >> 4) & 1) + 4 * (lane & 3);
;             const v4i16_t a0 = __builtin_amdgcn_ds_read_tr16_b64_v4i16((LAS v4i16_t*)(vrow)), a1 = __builtin_amdgcn_ds_read_tr16_b64_v4i16((LAS v4i16_t*)(vrow + 8 * AT_VLD));
;             const v4i16_t c0 = __builtin_amdgcn_ds_read_tr16_b64_v4i16((LAS v4i16_t*)(vrow + 32)), c1 = __builtin_amdgcn_ds_read_tr16_b64_v4i16((LAS v4i16_t*)(vrow + 8 * AT_VLD + 32));
;             const bf16x8 v0 = __builtin_shufflevector(a0, a1, 0, 1, 2, 3, 4, 5, 6, 7), v1 = __builtin_shufflevector(c0, c1, 0, 1, 2, 3, 4, 5, 6, 7);
;             o0 = MFMA32(pf[s4], v0, o0);
;             o1 = MFMA32(pf[s4], v1, o1);
;         }
;         lstoreK(buf); lstoreV(buf ^ 1);
.Lattn_nok1_b:
	s_waitcnt lgkmcnt(0)
	s_barrier
	s_add_i32 s13, s13, 2
	s_cmp_lt_u32 s13, 30
	s_cbranch_scc1 .Lattn_loop
	ds_read_b128 v[138:141], v168 offset:13312
	ds_read_b128 v[142:145], v168 offset:19968
	ds_read_b128 v[146:149], v168 offset:13344
	ds_read_b64_tr_b16 v[212:213], v170 offset:26624
	ds_read_b64_tr_b16 v[214:215], v170 offset:27776
	ds_read_b64_tr_b16 v[216:217], v170 offset:26688
	ds_read_b64_tr_b16 v[218:219], v170 offset:27840
	v_exp_f32_e32 v192, v50
	v_exp_f32_e32 v193, v51
	v_exp_f32_e32 v194, v52
	v_exp_f32_e32 v195, v53
	v_exp_f32_e32 v196, v54
	v_exp_f32_e32 v197, v55
	v_exp_f32_e32 v198, v56
	v_exp_f32_e32 v199, v57
	s_waitcnt lgkmcnt(6)
	v_mfma_f32_32x32x16_bf16 v[98:113], v[138:141], v[114:117], v[34:49]
	ds_read_b128 v[138:141], v168 offset:20000
	v_add_f32_e32 v173, v192, v193
	v_add_f32_e32 v174, v194, v195
	v_add_f32_e32 v173, v173, v196
	v_add_f32_e32 v174, v174, v197
	v_add_f32_e32 v173, v173, v198
	v_add_f32_e32 v174, v174, v199
	s_waitcnt lgkmcnt(6)
	v_mfma_f32_32x32x16_bf16 v[82:97], v[142:145], v[114:117], v[34:49]
	ds_read_b128 v[142:145], v168 offset:13376
	v_cvt_pk_bf16_f32 v176, v192, v193
	v_cvt_pk_bf16_f32 v177, v194, v195
	v_cvt_pk_bf16_f32 v178, v196, v197
	v_cvt_pk_bf16_f32 v179, v198, v199
	s_waitcnt lgkmcnt(6)
	v_mfma_f32_32x32x16_bf16 v[98:113], v[146:149], v[118:121], v[98:113]
	ds_read_b128 v[146:149], v168 offset:20032
	v_exp_f32_e32 v192, v58
	v_exp_f32_e32 v193, v59
	v_exp_f32_e32 v194, v60
	v_exp_f32_e32 v195, v61
	v_exp_f32_e32 v196, v62
	v_exp_f32_e32 v197, v63
	v_exp_f32_e32 v198, v64
	v_exp_f32_e32 v199, v65
	s_waitcnt lgkmcnt(5)
	v_mfma_f32_32x32x16_bf16 v[2:17], v[176:179], v[212:215], v[2:17]
	ds_read_b64_tr_b16 v[220:221], v170 offset:28928
	ds_read_b64_tr_b16 v[222:223], v170 offset:30080
	v_add_f32_e32 v173, v173, v192
	v_add_f32_e32 v174, v174, v193
	v_add_f32_e32 v173, v173, v194
	v_add_f32_e32 v174, v174, v195
	v_add_f32_e32 v173, v173, v196
	v_add_f32_e32 v174, v174, v197
	v_add_f32_e32 v173, v173, v198
	v_add_f32_e32 v174, v174, v199
	s_waitcnt lgkmcnt(5)
	v_mfma_f32_32x32x16_bf16 v[18:33], v[176:179], v[216:219], v[18:33]
	ds_read_b64_tr_b16 v[236:237], v170 offset:28992
	ds_read_b64_tr_b16 v[238:239], v170 offset:30144
	v_cvt_pk_bf16_f32 v180, v192, v193
	v_cvt_pk_bf16_f32 v181, v194, v195
	v_cvt_pk_bf16_f32 v182, v196, v197
	v_cvt_pk_bf16_f32 v183, v198, v199
	s_waitcnt lgkmcnt(6)
	v_mfma_f32_32x32x16_bf16 v[82:97], v[138:141], v[118:121], v[82:97]
	ds_read_b128 v[138:141], v168 offset:13408
	s_waitcnt lgkmcnt(6)
	v_mfma_f32_32x32x16_bf16 v[98:113], v[142:145], v[122:125], v[98:113]
	ds_read_b128 v[142:145], v168 offset:20064
	s_waitcnt lgkmcnt(6)
	v_mfma_f32_32x32x16_bf16 v[82:97], v[146:149], v[122:125], v[82:97]
	ds_read_b128 v[146:149], v168 offset:13440
	v_exp_f32_e32 v192, v66
	v_exp_f32_e32 v193, v67
	v_exp_f32_e32 v194, v68
	v_exp_f32_e32 v195, v69
	v_exp_f32_e32 v196, v70
	v_exp_f32_e32 v197, v71
	v_exp_f32_e32 v198, v72
	v_exp_f32_e32 v199, v73
	s_waitcnt lgkmcnt(5)
	v_mfma_f32_32x32x16_bf16 v[2:17], v[180:183], v[220:223], v[2:17]
	ds_read_b64_tr_b16 v[212:213], v170 offset:31232
	ds_read_b64_tr_b16 v[214:215], v170 offset:32384
	v_add_f32_e32 v173, v173, v192
	v_add_f32_e32 v174, v174, v193
	v_add_f32_e32 v173, v173, v194
	v_add_f32_e32 v174, v174, v195
	v_add_f32_e32 v173, v173, v196
	v_add_f32_e32 v174, v174, v197
	v_add_f32_e32 v173, v173, v198
	v_add_f32_e32 v174, v174, v199
	s_waitcnt lgkmcnt(5)
	v_mfma_f32_32x32x16_bf16 v[18:33], v[180:183], v[236:239], v[18:33]
	ds_read_b64_tr_b16 v[216:217], v170 offset:31296
	ds_read_b64_tr_b16 v[218:219], v170 offset:32448
	v_cvt_pk_bf16_f32 v184, v192, v193
	v_cvt_pk_bf16_f32 v185, v194, v195
	v_cvt_pk_bf16_f32 v186, v196, v197
	v_cvt_pk_bf16_f32 v187, v198, v199
	s_waitcnt lgkmcnt(6)
	v_mfma_f32_32x32x16_bf16 v[98:113], v[138:141], v[126:129], v[98:113]
	ds_read_b128 v[138:141], v168 offset:20096
	s_waitcnt lgkmcnt(6)
	v_mfma_f32_32x32x16_bf16 v[82:97], v[142:145], v[126:129], v[82:97]
	ds_read_b128 v[142:145], v168 offset:13472
	s_waitcnt lgkmcnt(6)
	v_mfma_f32_32x32x16_bf16 v[98:113], v[146:149], v[130:133], v[98:113]
	ds_read_b128 v[146:149], v168 offset:20128
	v_exp_f32_e32 v192, v74
	v_exp_f32_e32 v193, v75
	v_exp_f32_e32 v194, v76
	v_exp_f32_e32 v195, v77
	v_exp_f32_e32 v196, v78
	v_exp_f32_e32 v197, v79
	v_exp_f32_e32 v198, v80
	v_exp_f32_e32 v199, v81
	s_waitcnt lgkmcnt(5)
	v_mfma_f32_32x32x16_bf16 v[2:17], v[184:187], v[212:215], v[2:17]
	ds_read_b64_tr_b16 v[220:221], v170 offset:33536
	ds_read_b64_tr_b16 v[222:223], v170 offset:34688
	v_add_f32_e32 v173, v173, v192
	v_add_f32_e32 v174, v174, v193
	v_add_f32_e32 v173, v173, v194
	v_add_f32_e32 v174, v174, v195
	v_add_f32_e32 v173, v173, v196
	v_add_f32_e32 v174, v174, v197
	v_add_f32_e32 v173, v173, v198
	v_add_f32_e32 v174, v174, v199
	s_waitcnt lgkmcnt(5)
	v_mfma_f32_32x32x16_bf16 v[18:33], v[184:187], v[216:219], v[18:33]
	ds_read_b64_tr_b16 v[236:237], v170 offset:33600
	ds_read_b64_tr_b16 v[238:239], v170 offset:34752
	v_cvt_pk_bf16_f32 v188, v192, v193
	v_cvt_pk_bf16_f32 v189, v194, v195
	v_cvt_pk_bf16_f32 v190, v196, v197
	v_cvt_pk_bf16_f32 v191, v198, v199
	s_waitcnt lgkmcnt(6)
	v_mfma_f32_32x32x16_bf16 v[82:97], v[138:141], v[130:133], v[82:97]
	s_waitcnt lgkmcnt(5)
	v_mfma_f32_32x32x16_bf16 v[98:113], v[142:145], v[134:137], v[98:113]
	s_waitcnt lgkmcnt(4)
	v_mfma_f32_32x32x16_bf16 v[82:97], v[146:149], v[134:137], v[82:97]
	v_add_f32_e32 v172, v172, v173
	v_add_f32_e32 v172, v172, v174
	s_waitcnt lgkmcnt(2)
	v_mfma_f32_32x32x16_bf16 v[2:17], v[188:191], v[220:223], v[2:17]
	s_waitcnt vmcnt(0)
	ds_write_b128 v166, v[224:227]
	ds_write_b128 v167, v[232:235] offset:35840
	s_waitcnt lgkmcnt(2)
	v_mfma_f32_32x32x16_bf16 v[18:33], v[188:191], v[236:239], v[18:33]
	s_and_b64 vcc, exec, s[40:41]
	s_cbranch_vccz .Lattn_nok1_c
	ds_write_b128 v171, v[228:231]
; __device__ __forceinline__ void attn_unit(CArgs a, int layer, int unit, LAS unsigned char* lds) {
;     ...
;     auto tile = [&](int t, f32x16& c0, f32x16& c1, f32x16& n0, f32x16& n1) {
;         const int buf = t & 1;
;         gloadK(t + 2 < NT ? t + 2 : NT - 1); gloadV(t + 1 < NT ? t + 1 : NT - 1);
;         const LAS bf16_t* Vl = (const LAS bf16_t*)(lds + AT_V + buf * AT_VB);
;         if (t + 1 < NT) qk(buf ^ 1, n0, n1);
;         f32x16 p0, p1;
;         float rs = 0.f;
; #pragma unroll
;         for (int r = 0; r < 16; ++r) { p0[r] = __builtin_amdgcn_exp2f(c0[r]); p1[r] = __builtin_amdgcn_exp2f(c1[r]); rs += p0[r] + p1[r]; }
;         lrun += rs;
;         bf16x8 pf[4];
; #pragma unroll
;         for (int s = 0; s < 2; ++s) {
;             u32x4 w0, w1;
;             w0.x = cvt_pk_bf16(p0[8 * s], p0[8 * s + 1]); w0.y = cvt_pk_bf16(p0[8 * s + 2], p0[8 * s + 3]); w0.z = cvt_pk_bf16(p0[8 * s + 4], p0[8 * s + 5]); w0.w = cvt_pk_bf16(p0[8 * s + 6], p0[8 * s + 7]);
;             w1.x = cvt_pk_bf16(p1[8 * s], p1[8 * s + 1]); w1.y = cvt_pk_bf16(p1[8 * s + 2], p1[8 * s + 3]); w1.z = cvt_pk_bf16(p1[8 * s + 4], p1[8 * s + 5]); w1.w = cvt_pk_bf16(p1[8 * s + 6], p1[8 * s + 7]);
;             pf[s] = __builtin_bit_cast(bf16x8, w0); pf[2 + s] = __builtin_bit_cast(bf16x8, w1);
;         }
; #pragma unroll
;         for (int i = 0; i < 12; ++i) { __builtin_amdgcn_sched_group_barrier(0x008, 1, 0); __builtin_amdgcn_sched_group_barrier(0x002, 9, 0); }
; #pragma unroll
;         for (int s4 = 0; s4 < 4; ++s4) {
;             const int kb = 32 * (s4 >> 1) + 16 * (s4 & 1) + 4 * hi;
;             const LAS bf16_t* vrow = Vl + (kb - 4 * hi + 4 * hi + ((lane & 15) >> 2)) * AT_VLD + 16 * ((lane >> 4) & 1) + 4 * (lane & 3);
;             const v4i16_t a0 = __builtin_amdgcn_ds_read_tr16_b64_v4i16((LAS v4i16_t*)(vrow)), a1 = __builtin_amdgcn_ds_read_tr16_b64_v4i16((LAS v4i16_t*)(vrow + 8 * AT_VLD));
;             const v4i16_t c0 = __builtin_amdgcn_ds_read_tr16_b64_v4i16((LAS v4i16_t*)(vrow + 32)), c1 = __builtin_amdgcn_ds_read_tr16_b64_v4i16((LAS v4i16_t*)(vrow + 8 * AT_VLD + 32));
;             const bf16x8 v0 = __builtin_shufflevector(a0, a1, 0, 1, 2, 3, 4, 5, 6, 7), v1 = __builtin_shufflevector(c0, c1, 0, 1, 2, 3, 4, 5, 6, 7);
;             o0 = MFMA32(pf[s4], v0, o0);
;             o1 = MFMA32(pf[s4], v1, o1);
;         }
;         lstoreK(buf); lstoreV(buf ^ 1);
.Lattn_nok1_c:
	s_waitcnt lgkmcnt(0)
	s_barrier
	ds_read_b64_tr_b16 v[212:213], v170 offset:35840
	ds_read_b64_tr_b16 v[214:215], v170 offset:36992
	ds_read_b64_tr_b16 v[216:217], v170 offset:35904
	ds_read_b64_tr_b16 v[218:219], v170 offset:37056
	v_exp_f32_e32 v192, v98
	v_exp_f32_e32 v193, v99
	v_exp_f32_e32 v194, v100
	v_exp_f32_e32 v195, v101
	v_exp_f32_e32 v196, v102
	v_exp_f32_e32 v197, v103
	v_exp_f32_e32 v198, v104
	v_exp_f32_e32 v199, v105
	v_add_f32_e32 v173, v192, v193
	v_add_f32_e32 v174, v194, v195
	v_add_f32_e32 v173, v173, v196
	v_add_f32_e32 v174, v174, v197
	v_add_f32_e32 v173, v173, v198
	v_add_f32_e32 v174, v174, v199
	v_cvt_pk_bf16_f32 v176, v192, v193
	v_cvt_pk_bf16_f32 v177, v194, v195
	v_cvt_pk_bf16_f32 v178, v196, v197
	v_cvt_pk_bf16_f32 v179, v198, v199
	v_exp_f32_e32 v192, v106
	v_exp_f32_e32 v193, v107
	v_exp_f32_e32 v194, v108
	v_exp_f32_e32 v195, v109
	v_exp_f32_e32 v196, v110
	v_exp_f32_e32 v197, v111
	v_exp_f32_e32 v198, v112
	v_exp_f32_e32 v199, v113
	s_waitcnt lgkmcnt(2)
	v_mfma_f32_32x32x16_bf16 v[2:17], v[176:179], v[212:215], v[2:17]
	ds_read_b64_tr_b16 v[220:221], v170 offset:38144
	ds_read_b64_tr_b16 v[222:223], v170 offset:39296
	v_add_f32_e32 v173, v173, v192
	v_add_f32_e32 v174, v174, v193
	v_add_f32_e32 v173, v173, v194
	v_add_f32_e32 v174, v174, v195
	v_add_f32_e32 v173, v173, v196
	v_add_f32_e32 v174, v174, v197
	v_add_f32_e32 v173, v173, v198
	v_add_f32_e32 v174, v174, v199
	s_waitcnt lgkmcnt(2)
	v_mfma_f32_32x32x16_bf16 v[18:33], v[176:179], v[216:219], v[18:33]
	ds_read_b64_tr_b16 v[236:237], v170 offset:38208
	ds_read_b64_tr_b16 v[238:239], v170 offset:39360
	v_cvt_pk_bf16_f32 v180, v192, v193
	v_cvt_pk_bf16_f32 v181, v194, v195
	v_cvt_pk_bf16_f32 v182, v196, v197
	v_cvt_pk_bf16_f32 v183, v198, v199
	v_exp_f32_e32 v192, v82
	v_exp_f32_e32 v193, v83
	v_exp_f32_e32 v194, v84
	v_exp_f32_e32 v195, v85
	v_exp_f32_e32 v196, v86
	v_exp_f32_e32 v197, v87
	v_exp_f32_e32 v198, v88
	v_exp_f32_e32 v199, v89
	s_waitcnt lgkmcnt(2)
	v_mfma_f32_32x32x16_bf16 v[2:17], v[180:183], v[220:223], v[2:17]
	ds_read_b64_tr_b16 v[212:213], v170 offset:40448
	ds_read_b64_tr_b16 v[214:215], v170 offset:41600
	v_add_f32_e32 v173, v173, v192
	v_add_f32_e32 v174, v174, v193
	v_add_f32_e32 v173, v173, v194
	v_add_f32_e32 v174, v174, v195
	v_add_f32_e32 v173, v173, v196
	v_add_f32_e32 v174, v174, v197
	v_add_f32_e32 v173, v173, v198
	v_add_f32_e32 v174, v174, v199
	s_waitcnt lgkmcnt(2)
	v_mfma_f32_32x32x16_bf16 v[18:33], v[180:183], v[236:239], v[18:33]
	ds_read_b64_tr_b16 v[216:217], v170 offset:40512
	ds_read_b64_tr_b16 v[218:219], v170 offset:41664
	v_cvt_pk_bf16_f32 v184, v192, v193
	v_cvt_pk_bf16_f32 v185, v194, v195
	v_cvt_pk_bf16_f32 v186, v196, v197
	v_cvt_pk_bf16_f32 v187, v198, v199
	v_exp_f32_e32 v192, v90
	v_exp_f32_e32 v193, v91
	v_exp_f32_e32 v194, v92
	v_exp_f32_e32 v195, v93
	v_exp_f32_e32 v196, v94
	v_exp_f32_e32 v197, v95
	v_exp_f32_e32 v198, v96
	v_exp_f32_e32 v199, v97
	s_waitcnt lgkmcnt(2)
	v_mfma_f32_32x32x16_bf16 v[2:17], v[184:187], v[212:215], v[2:17]
	ds_read_b64_tr_b16 v[220:221], v170 offset:42752
	ds_read_b64_tr_b16 v[222:223], v170 offset:43904
	v_add_f32_e32 v173, v173, v192
	v_add_f32_e32 v174, v174, v193
	v_add_f32_e32 v173, v173, v194
	v_add_f32_e32 v174, v174, v195
	v_add_f32_e32 v173, v173, v196
	v_add_f32_e32 v174, v174, v197
	v_add_f32_e32 v173, v173, v198
	v_add_f32_e32 v174, v174, v199
	s_waitcnt lgkmcnt(2)
	v_mfma_f32_32x32x16_bf16 v[18:33], v[184:187], v[216:219], v[18:33]
	ds_read_b64_tr_b16 v[236:237], v170 offset:42816
	ds_read_b64_tr_b16 v[238:239], v170 offset:43968
	v_cvt_pk_bf16_f32 v188, v192, v193
	v_cvt_pk_bf16_f32 v189, v194, v195
	v_cvt_pk_bf16_f32 v190, v196, v197
	v_cvt_pk_bf16_f32 v191, v198, v199
	v_add_f32_e32 v172, v172, v173
	v_add_f32_e32 v172, v172, v174
	s_waitcnt lgkmcnt(2)
	v_mfma_f32_32x32x16_bf16 v[2:17], v[188:191], v[220:223], v[2:17]
	s_waitcnt lgkmcnt(0)
	v_mfma_f32_32x32x16_bf16 v[18:33], v[188:191], v[236:239], v[18:33]
	s_waitcnt lgkmcnt(0)
	s_barrier
